# SwiGLU epilogue: same f32 math with fewer VALU ops (packed t=g*c, packed 1+e, (g*u)*rstd^2*r), u64 row-stat to f32 via cvt hi/lo + fma
# speedup vs baseline: 1.0445x; 1.0068x over previous
; __device__ __forceinline__ float row_rs(const float* ssp, int row) { const unsigned long long v = ((const unsigned long long*)ssp)[row];
;     return __builtin_amdgcn_rsqf((float)v * (1.0f / 4294967296.0f) * (1.0f / 1024.0f) + RMS_EPS); }
; __device__ __forceinline__ void fx_add(float* p, size_t idx, float s) { atomicAdd((unsigned long long*)p + idx, (unsigned long long)(long long)(s * 4294967296.0f)); }
; __device__ __forceinline__ unsigned cvtpk(float lo, float hi) { f32x2v_ v = {lo, hi}; bf16x2v_ b = __builtin_convertvector(v, bf16x2v_); return __builtin_bit_cast(unsigned, b); }
;     __device__ __forceinline__ void operator()(const f32x4 (&acc)[2][2][4][2], const Unit& u, int wr, int wc, int fr, int fq) const {
;         const int row0 = u.pm * BM + wr * 64 + fr, col0 = u.pn * HALF + wc * 32 + 8 * fq;
; #pragma unroll
;         for (int ai = 0; ai < 2; ++ai)
; #pragma unroll
;             for (int m = 0; m < 4; ++m) { const int row = row0 + ai * HALF + m * 16; const float rs = row_rs(ss, row);
;                 float hv[8];
; #pragma unroll
;                 for (int n = 0; n < 2; ++n)
; #pragma unroll
;                     for (int i = 0; i < 4; ++i) { const float g = acc[ai][0][m][n][i] * rs, uu = acc[ai][1][m][n][i] * rs;
;                         hv[n * 4 + i] = g * __builtin_amdgcn_rcpf(1.0f + __expf(-g)) * uu; }
;                 u32x4 w; w.x = cvtpk(hv[0], hv[1]); w.y = cvtpk(hv[2], hv[3]); w.z = cvtpk(hv[4], hv[5]); w.w = cvtpk(hv[6], hv[7]);
;                 *(u32x4*)(H + (size_t)row * ldh + col0) = w; }
.LBB0_194:
	v_lshl_or_b32 v160, s66, 7, v154
	v_ashrrev_i32_e32 v161, 31, v160
	v_or_b32_e32 v164, 16, v144
	v_ashrrev_i32_e32 v165, 31, v164
	v_lshl_add_u64 v[168:169], v[164:165], 3, s[6:7]
	v_mov_b64_e32 v[146:147], s[20:21]
	v_mad_i64_i32 v[162:163], s[14:15], v144, s65, v[146:147]
	s_andn2_b64 vcc, exec, s[0:1]
	s_mov_b64 s[0:1], -1
	s_waitcnt vmcnt(7)
	v_cvt_f32_u32_e32 v159, v183
	v_cvt_f32_u32_e32 v145, v182
	v_lshlrev_b64 v[148:149], 1, v[160:161]
	v_lshl_add_u64 v[162:163], v[162:163], 0, v[148:149]
	v_fmamk_f32 v145, v145, 0x2f800000, v159
	v_fmamk_f32 v145, v145, 0x3a800000, v158
	v_rsq_f32_e32 v160, v145
	s_nop 0
	v_mul_f32_e32 v182, 0xbfb8aa3b, v160
	v_mul_f32_e32 v183, v160, v160
	v_pk_mul_f32 v[160:161], v[124:125], v[182:183] op_sel_hi:[1,0]
	v_pk_mul_f32 v[170:171], v[126:127], v[182:183] op_sel_hi:[1,0]
	v_pk_mul_f32 v[172:173], v[120:121], v[182:183] op_sel_hi:[1,0]
	v_pk_mul_f32 v[174:175], v[122:123], v[182:183] op_sel_hi:[1,0]
	v_pk_mul_f32 v[116:117], v[116:117], v[124:125]
	v_pk_mul_f32 v[118:119], v[118:119], v[126:127]
	v_pk_mul_f32 v[120:121], v[112:113], v[120:121]
	v_pk_mul_f32 v[122:123], v[114:115], v[122:123]
	v_exp_f32_e32 v160, v160
	v_exp_f32_e32 v161, v161
	v_exp_f32_e32 v170, v170
	v_exp_f32_e32 v171, v171
	v_exp_f32_e32 v172, v172
	v_exp_f32_e32 v173, v173
	v_exp_f32_e32 v174, v174
	v_exp_f32_e32 v175, v175
	v_pk_mul_f32 v[116:117], v[116:117], v[182:183] op_sel:[0,1] op_sel_hi:[1,1]
	v_pk_mul_f32 v[118:119], v[118:119], v[182:183] op_sel:[0,1] op_sel_hi:[1,1]
	v_pk_mul_f32 v[120:121], v[120:121], v[182:183] op_sel:[0,1] op_sel_hi:[1,1]
	v_pk_mul_f32 v[122:123], v[122:123], v[182:183] op_sel:[0,1] op_sel_hi:[1,1]
	v_pk_add_f32 v[160:161], v[160:161], 1.0 op_sel_hi:[1,0]
	v_pk_add_f32 v[170:171], v[170:171], 1.0 op_sel_hi:[1,0]
	v_pk_add_f32 v[172:173], v[172:173], 1.0 op_sel_hi:[1,0]
	v_pk_add_f32 v[174:175], v[174:175], 1.0 op_sel_hi:[1,0]
	v_rcp_f32_e32 v160, v160
	v_rcp_f32_e32 v161, v161
	v_rcp_f32_e32 v170, v170
	v_rcp_f32_e32 v171, v171
	v_rcp_f32_e32 v172, v172
	v_rcp_f32_e32 v173, v173
	v_rcp_f32_e32 v174, v174
	v_rcp_f32_e32 v175, v175
	v_pk_mul_f32 v[116:117], v[116:117], v[160:161]
	v_pk_mul_f32 v[118:119], v[118:119], v[170:171]
	v_pk_mul_f32 v[120:121], v[120:121], v[172:173]
	v_pk_mul_f32 v[122:123], v[122:123], v[174:175]
	v_cvt_pk_bf16_f32 v112, v116, v117
	v_cvt_pk_bf16_f32 v113, v118, v119
	v_cvt_pk_bf16_f32 v114, v120, v121
	v_cvt_pk_bf16_f32 v115, v122, v123
	global_store_dwordx4 v[162:163], v[112:115], off
	s_nop 0
	s_nop 0
	v_or_b32_e32 v114, 32, v144
	s_waitcnt vmcnt(7)
	v_cvt_f32_u32_e32 v116, v185
	v_cvt_f32_u32_e32 v115, v184
	v_mad_i64_i32 v[112:113], s[14:15], v164, s65, v[146:147]
	v_fmamk_f32 v115, v115, 0x2f800000, v116
	v_fmamk_f32 v115, v115, 0x3a800000, v158
	v_rsq_f32_e32 v116, v115
	v_ashrrev_i32_e32 v115, 31, v114
	v_lshl_add_u64 v[118:119], v[114:115], 3, s[6:7]
	v_lshl_add_u64 v[112:113], v[112:113], 0, v[148:149]
	v_mul_f32_e32 v184, 0xbfb8aa3b, v116
	v_mul_f32_e32 v185, v116, v116
	v_pk_mul_f32 v[116:117], v[108:109], v[184:185] op_sel_hi:[1,0]
	v_pk_mul_f32 v[120:121], v[110:111], v[184:185] op_sel_hi:[1,0]
	v_pk_mul_f32 v[122:123], v[104:105], v[184:185] op_sel_hi:[1,0]
	v_pk_mul_f32 v[124:125], v[106:107], v[184:185] op_sel_hi:[1,0]
	v_pk_mul_f32 v[100:101], v[100:101], v[108:109]
	v_pk_mul_f32 v[102:103], v[102:103], v[110:111]
	v_pk_mul_f32 v[104:105], v[96:97], v[104:105]
	v_pk_mul_f32 v[106:107], v[98:99], v[106:107]
	v_exp_f32_e32 v116, v116
	v_exp_f32_e32 v117, v117
	v_exp_f32_e32 v120, v120
	v_exp_f32_e32 v121, v121
	v_exp_f32_e32 v122, v122
	v_exp_f32_e32 v123, v123
	v_exp_f32_e32 v124, v124
	v_exp_f32_e32 v125, v125
	v_pk_mul_f32 v[100:101], v[100:101], v[184:185] op_sel:[0,1] op_sel_hi:[1,1]
	v_pk_mul_f32 v[102:103], v[102:103], v[184:185] op_sel:[0,1] op_sel_hi:[1,1]
	v_pk_mul_f32 v[104:105], v[104:105], v[184:185] op_sel:[0,1] op_sel_hi:[1,1]
	v_pk_mul_f32 v[106:107], v[106:107], v[184:185] op_sel:[0,1] op_sel_hi:[1,1]
	v_pk_add_f32 v[116:117], v[116:117], 1.0 op_sel_hi:[1,0]
	v_pk_add_f32 v[120:121], v[120:121], 1.0 op_sel_hi:[1,0]
	v_pk_add_f32 v[122:123], v[122:123], 1.0 op_sel_hi:[1,0]
	v_pk_add_f32 v[124:125], v[124:125], 1.0 op_sel_hi:[1,0]
	v_rcp_f32_e32 v116, v116
	v_rcp_f32_e32 v117, v117
	v_rcp_f32_e32 v120, v120
	v_rcp_f32_e32 v121, v121
	v_rcp_f32_e32 v122, v122
	v_rcp_f32_e32 v123, v123
	v_rcp_f32_e32 v124, v124
	v_rcp_f32_e32 v125, v125
	v_pk_mul_f32 v[100:101], v[100:101], v[116:117]
	v_pk_mul_f32 v[102:103], v[102:103], v[120:121]
	v_pk_mul_f32 v[104:105], v[104:105], v[122:123]
	v_pk_mul_f32 v[106:107], v[106:107], v[124:125]
	v_cvt_pk_bf16_f32 v96, v100, v101
	v_cvt_pk_bf16_f32 v97, v102, v103
	v_cvt_pk_bf16_f32 v98, v104, v105
	v_cvt_pk_bf16_f32 v99, v106, v107
	global_store_dwordx4 v[112:113], v[96:99], off
	s_nop 0
	s_nop 0
	v_or_b32_e32 v98, 48, v144
	s_waitcnt vmcnt(7)
; __device__ __forceinline__ float row_rs(const float* ssp, int row) { const unsigned long long v = ((const unsigned long long*)ssp)[row];
;     return __builtin_amdgcn_rsqf((float)v * (1.0f / 4294967296.0f) * (1.0f / 1024.0f) + RMS_EPS); }
; __device__ __forceinline__ void fx_add(float* p, size_t idx, float s) { atomicAdd((unsigned long long*)p + idx, (unsigned long long)(long long)(s * 4294967296.0f)); }
; __device__ __forceinline__ unsigned cvtpk(float lo, float hi) { f32x2v_ v = {lo, hi}; bf16x2v_ b = __builtin_convertvector(v, bf16x2v_); return __builtin_bit_cast(unsigned, b); }
;     __device__ __forceinline__ void operator()(const f32x4 (&acc)[2][2][4][2], const Unit& u, int wr, int wc, int fr, int fq) const {
;         const int row0 = u.pm * BM + wr * 64 + fr, col0 = u.pn * HALF + wc * 32 + 8 * fq;
; #pragma unroll
;         for (int ai = 0; ai < 2; ++ai)
; #pragma unroll
;             for (int m = 0; m < 4; ++m) { const int row = row0 + ai * HALF + m * 16; const float rs = row_rs(ss, row);
;                 float hv[8];
; #pragma unroll
;                 for (int n = 0; n < 2; ++n)
; #pragma unroll
;                     for (int i = 0; i < 4; ++i) { const float g = acc[ai][0][m][n][i] * rs, uu = acc[ai][1][m][n][i] * rs;
;                         hv[n * 4 + i] = g * __builtin_amdgcn_rcpf(1.0f + __expf(-g)) * uu; }
;                 u32x4 w; w.x = cvtpk(hv[0], hv[1]); w.y = cvtpk(hv[2], hv[3]); w.z = cvtpk(hv[4], hv[5]); w.w = cvtpk(hv[6], hv[7]);
;                 *(u32x4*)(H + (size_t)row * ldh + col0) = w; }
	v_cvt_f32_u32_e32 v100, v187
	v_cvt_f32_u32_e32 v99, v186
	v_mad_i64_i32 v[96:97], s[14:15], v114, s65, v[146:147]
	v_fmamk_f32 v99, v99, 0x2f800000, v100
	v_fmamk_f32 v99, v99, 0x3a800000, v158
	v_rsq_f32_e32 v100, v99
	v_ashrrev_i32_e32 v99, 31, v98
	v_lshl_add_u64 v[102:103], v[98:99], 3, s[6:7]
	v_lshl_add_u64 v[96:97], v[96:97], 0, v[148:149]
	v_mul_f32_e32 v186, 0xbfb8aa3b, v100
	v_mul_f32_e32 v187, v100, v100
	v_pk_mul_f32 v[100:101], v[92:93], v[186:187] op_sel_hi:[1,0]
	v_pk_mul_f32 v[104:105], v[94:95], v[186:187] op_sel_hi:[1,0]
	v_pk_mul_f32 v[106:107], v[88:89], v[186:187] op_sel_hi:[1,0]
	v_pk_mul_f32 v[108:109], v[90:91], v[186:187] op_sel_hi:[1,0]
	v_pk_mul_f32 v[84:85], v[84:85], v[92:93]
	v_pk_mul_f32 v[86:87], v[86:87], v[94:95]
	v_pk_mul_f32 v[88:89], v[80:81], v[88:89]
	v_pk_mul_f32 v[90:91], v[82:83], v[90:91]
	v_exp_f32_e32 v100, v100
	v_exp_f32_e32 v101, v101
	v_exp_f32_e32 v104, v104
	v_exp_f32_e32 v105, v105
	v_exp_f32_e32 v106, v106
	v_exp_f32_e32 v107, v107
	v_exp_f32_e32 v108, v108
	v_exp_f32_e32 v109, v109
	v_pk_mul_f32 v[84:85], v[84:85], v[186:187] op_sel:[0,1] op_sel_hi:[1,1]
	v_pk_mul_f32 v[86:87], v[86:87], v[186:187] op_sel:[0,1] op_sel_hi:[1,1]
	v_pk_mul_f32 v[88:89], v[88:89], v[186:187] op_sel:[0,1] op_sel_hi:[1,1]
	v_pk_mul_f32 v[90:91], v[90:91], v[186:187] op_sel:[0,1] op_sel_hi:[1,1]
	v_pk_add_f32 v[100:101], v[100:101], 1.0 op_sel_hi:[1,0]
	v_pk_add_f32 v[104:105], v[104:105], 1.0 op_sel_hi:[1,0]
	v_pk_add_f32 v[106:107], v[106:107], 1.0 op_sel_hi:[1,0]
	v_pk_add_f32 v[108:109], v[108:109], 1.0 op_sel_hi:[1,0]
	v_rcp_f32_e32 v100, v100
	v_rcp_f32_e32 v101, v101
	v_rcp_f32_e32 v104, v104
	v_rcp_f32_e32 v105, v105
	v_rcp_f32_e32 v106, v106
	v_rcp_f32_e32 v107, v107
	v_rcp_f32_e32 v108, v108
	v_rcp_f32_e32 v109, v109
	v_pk_mul_f32 v[84:85], v[84:85], v[100:101]
	v_pk_mul_f32 v[86:87], v[86:87], v[104:105]
	v_pk_mul_f32 v[88:89], v[88:89], v[106:107]
	v_pk_mul_f32 v[90:91], v[90:91], v[108:109]
	v_cvt_pk_bf16_f32 v80, v84, v85
	v_cvt_pk_bf16_f32 v81, v86, v87
	v_cvt_pk_bf16_f32 v82, v88, v89
	v_cvt_pk_bf16_f32 v83, v90, v91
	global_store_dwordx4 v[96:97], v[80:83], off
	s_nop 0
	s_waitcnt vmcnt(7)
	v_cvt_f32_u32_e32 v80, v189
	v_cvt_f32_u32_e32 v81, v188
	v_mad_i64_i32 v[82:83], s[14:15], v98, s65, v[146:147]
	v_fmamk_f32 v80, v81, 0x2f800000, v80
	v_fmamk_f32 v80, v80, 0x3a800000, v158
	v_rsq_f32_e32 v80, v80
	v_lshl_add_u64 v[82:83], v[82:83], 0, v[148:149]
	v_mul_f32_e32 v188, 0xbfb8aa3b, v80
	v_mul_f32_e32 v189, v80, v80
	v_pk_mul_f32 v[80:81], v[76:77], v[188:189] op_sel_hi:[1,0]
	v_pk_mul_f32 v[84:85], v[78:79], v[188:189] op_sel_hi:[1,0]
	v_pk_mul_f32 v[86:87], v[72:73], v[188:189] op_sel_hi:[1,0]
	v_pk_mul_f32 v[88:89], v[74:75], v[188:189] op_sel_hi:[1,0]
	v_pk_mul_f32 v[68:69], v[68:69], v[76:77]
	v_pk_mul_f32 v[70:71], v[70:71], v[78:79]
	v_pk_mul_f32 v[72:73], v[64:65], v[72:73]
	v_pk_mul_f32 v[74:75], v[66:67], v[74:75]
	v_exp_f32_e32 v80, v80
	v_exp_f32_e32 v81, v81
	v_exp_f32_e32 v84, v84
	v_exp_f32_e32 v85, v85
	v_exp_f32_e32 v86, v86
	v_exp_f32_e32 v87, v87
	v_exp_f32_e32 v88, v88
	v_exp_f32_e32 v89, v89
	v_pk_mul_f32 v[68:69], v[68:69], v[188:189] op_sel:[0,1] op_sel_hi:[1,1]
	v_pk_mul_f32 v[70:71], v[70:71], v[188:189] op_sel:[0,1] op_sel_hi:[1,1]
	v_pk_mul_f32 v[72:73], v[72:73], v[188:189] op_sel:[0,1] op_sel_hi:[1,1]
	v_pk_mul_f32 v[74:75], v[74:75], v[188:189] op_sel:[0,1] op_sel_hi:[1,1]
	v_pk_add_f32 v[80:81], v[80:81], 1.0 op_sel_hi:[1,0]
	v_pk_add_f32 v[84:85], v[84:85], 1.0 op_sel_hi:[1,0]
	v_pk_add_f32 v[86:87], v[86:87], 1.0 op_sel_hi:[1,0]
	v_pk_add_f32 v[88:89], v[88:89], 1.0 op_sel_hi:[1,0]
	v_rcp_f32_e32 v80, v80
	v_rcp_f32_e32 v81, v81
	v_rcp_f32_e32 v84, v84
	v_rcp_f32_e32 v85, v85
	v_rcp_f32_e32 v86, v86
	v_rcp_f32_e32 v87, v87
	v_rcp_f32_e32 v88, v88
	v_rcp_f32_e32 v89, v89
	v_pk_mul_f32 v[68:69], v[68:69], v[80:81]
	v_pk_mul_f32 v[70:71], v[70:71], v[84:85]
	v_pk_mul_f32 v[72:73], v[72:73], v[86:87]
	v_pk_mul_f32 v[74:75], v[74:75], v[88:89]
	v_cvt_pk_bf16_f32 v64, v68, v69
	v_cvt_pk_bf16_f32 v65, v70, v71
	v_cvt_pk_bf16_f32 v66, v72, v73
	v_cvt_pk_bf16_f32 v67, v74, v75
	global_store_dwordx4 v[82:83], v[64:67], off
	s_nop 0
	s_waitcnt vmcnt(7)
	v_cvt_f32_u32_e32 v64, v191
	v_cvt_f32_u32_e32 v66, v190
	v_add_u32_e32 v65, 0x80, v144
	v_fmamk_f32 v64, v66, 0x2f800000, v64
	v_fmamk_f32 v64, v64, 0x3a800000, v158
	v_rsq_f32_e32 v64, v64
	v_mad_i64_i32 v[66:67], s[14:15], v65, s65, v[146:147]
	v_lshl_add_u64 v[66:67], v[66:67], 0, v[148:149]
	v_mul_f32_e32 v190, 0xbfb8aa3b, v64
	v_mul_f32_e32 v191, v64, v64
	v_pk_mul_f32 v[64:65], v[60:61], v[190:191] op_sel_hi:[1,0]
	v_pk_mul_f32 v[68:69], v[62:63], v[190:191] op_sel_hi:[1,0]
	v_pk_mul_f32 v[70:71], v[56:57], v[190:191] op_sel_hi:[1,0]
	v_pk_mul_f32 v[72:73], v[58:59], v[190:191] op_sel_hi:[1,0]
	v_pk_mul_f32 v[52:53], v[52:53], v[60:61]
	v_pk_mul_f32 v[54:55], v[54:55], v[62:63]
	v_pk_mul_f32 v[56:57], v[48:49], v[56:57]
	v_pk_mul_f32 v[58:59], v[50:51], v[58:59]
	v_exp_f32_e32 v64, v64
	v_exp_f32_e32 v65, v65
	v_exp_f32_e32 v68, v68
	v_exp_f32_e32 v69, v69
	v_exp_f32_e32 v70, v70
	v_exp_f32_e32 v71, v71
	v_exp_f32_e32 v72, v72
	v_exp_f32_e32 v73, v73
	v_pk_mul_f32 v[52:53], v[52:53], v[190:191] op_sel:[0,1] op_sel_hi:[1,1]
	v_pk_mul_f32 v[54:55], v[54:55], v[190:191] op_sel:[0,1] op_sel_hi:[1,1]
	v_pk_mul_f32 v[56:57], v[56:57], v[190:191] op_sel:[0,1] op_sel_hi:[1,1]
	v_pk_mul_f32 v[58:59], v[58:59], v[190:191] op_sel:[0,1] op_sel_hi:[1,1]
	v_pk_add_f32 v[64:65], v[64:65], 1.0 op_sel_hi:[1,0]
	v_pk_add_f32 v[68:69], v[68:69], 1.0 op_sel_hi:[1,0]
	v_pk_add_f32 v[70:71], v[70:71], 1.0 op_sel_hi:[1,0]
	v_pk_add_f32 v[72:73], v[72:73], 1.0 op_sel_hi:[1,0]
	v_rcp_f32_e32 v64, v64
	v_rcp_f32_e32 v65, v65
	v_rcp_f32_e32 v68, v68
	v_rcp_f32_e32 v69, v69
	v_rcp_f32_e32 v70, v70
	v_rcp_f32_e32 v71, v71
	v_rcp_f32_e32 v72, v72
	v_rcp_f32_e32 v73, v73
	v_pk_mul_f32 v[52:53], v[52:53], v[64:65]
	v_pk_mul_f32 v[54:55], v[54:55], v[68:69]
	v_pk_mul_f32 v[56:57], v[56:57], v[70:71]
	v_pk_mul_f32 v[58:59], v[58:59], v[72:73]
	v_cvt_pk_bf16_f32 v48, v52, v53
	v_cvt_pk_bf16_f32 v49, v54, v55
	v_cvt_pk_bf16_f32 v50, v56, v57
	v_cvt_pk_bf16_f32 v51, v58, v59
	global_store_dwordx4 v[66:67], v[48:51], off
	s_nop 0
	s_waitcnt vmcnt(7)
; __device__ __forceinline__ unsigned cvtpk(float lo, float hi) { f32x2v_ v = {lo, hi}; bf16x2v_ b = __builtin_convertvector(v, bf16x2v_); return __builtin_bit_cast(unsigned, b); }
; #define PG8_BAR __builtin_amdgcn_s_barrier()
;     __device__ __forceinline__ void operator()(const f32x4 (&acc)[2][2][4][2], const Unit& u, int wr, int wc, int fr, int fq) const {
;     ...
;             for (int m = 0; m < 4; ++m) { const int row = row0 + ai * HALF + m * 16; const float rs = row_rs(ss, row);
;                 float hv[8];
; #pragma unroll
;                 for (int n = 0; n < 2; ++n)
; #pragma unroll
;                     for (int i = 0; i < 4; ++i) { const float g = acc[ai][0][m][n][i] * rs, uu = acc[ai][1][m][n][i] * rs;
;                         hv[n * 4 + i] = g * __builtin_amdgcn_rcpf(1.0f + __expf(-g)) * uu; }
;                 u32x4 w; w.x = cvtpk(hv[0], hv[1]); w.y = cvtpk(hv[2], hv[3]); w.z = cvtpk(hv[4], hv[5]); w.w = cvtpk(hv[6], hv[7]);
;                 *(u32x4*)(H + (size_t)row * ldh + col0) = w; }
; template <class Epi, class Sched, bool ALIGN_EPI = false, bool SP2 = false>
; __device__ __forceinline__ void gemm_phase(PG8_LAS unsigned char* lds, const Gemm g, const Sched& S, const Epi& E) {
;     ...
;         if (!has_next) break;
; #pragma unroll
;         for (int a = 0; a < 2; ++a)
; #pragma unroll
;             for (int b = 0; b < 2; ++b)
; #pragma unroll
;                 for (int m = 0; m < 4; ++m)
; #pragma unroll
;                     for (int n = 0; n < 2; ++n) acc[a][b][m][n] = (f32x4){0.f, 0.f, 0.f, 0.f};
;         cur = nxt; cA = nA; cB = nB; ++ui;
;         if constexpr (ALIGN_EPI) { if (wr == 1) PG8_BAR; }
	v_cvt_f32_u32_e32 v48, v193
	v_cvt_f32_u32_e32 v50, v192
	v_add_u32_e32 v49, 0x90, v144
	v_fmamk_f32 v48, v50, 0x2f800000, v48
	v_fmamk_f32 v48, v48, 0x3a800000, v158
	v_rsq_f32_e32 v48, v48
	v_mad_i64_i32 v[50:51], s[14:15], v49, s65, v[146:147]
	v_lshl_add_u64 v[50:51], v[50:51], 0, v[148:149]
	v_mul_f32_e32 v192, 0xbfb8aa3b, v48
	v_mul_f32_e32 v193, v48, v48
	v_pk_mul_f32 v[48:49], v[44:45], v[192:193] op_sel_hi:[1,0]
	v_pk_mul_f32 v[52:53], v[46:47], v[192:193] op_sel_hi:[1,0]
	v_pk_mul_f32 v[54:55], v[40:41], v[192:193] op_sel_hi:[1,0]
	v_pk_mul_f32 v[56:57], v[42:43], v[192:193] op_sel_hi:[1,0]
	v_pk_mul_f32 v[36:37], v[36:37], v[44:45]
	v_pk_mul_f32 v[38:39], v[38:39], v[46:47]
	v_pk_mul_f32 v[40:41], v[32:33], v[40:41]
	v_pk_mul_f32 v[42:43], v[34:35], v[42:43]
	v_exp_f32_e32 v48, v48
	v_exp_f32_e32 v49, v49
	v_exp_f32_e32 v52, v52
	v_exp_f32_e32 v53, v53
	v_exp_f32_e32 v54, v54
	v_exp_f32_e32 v55, v55
	v_exp_f32_e32 v56, v56
	v_exp_f32_e32 v57, v57
	v_pk_mul_f32 v[36:37], v[36:37], v[192:193] op_sel:[0,1] op_sel_hi:[1,1]
	v_pk_mul_f32 v[38:39], v[38:39], v[192:193] op_sel:[0,1] op_sel_hi:[1,1]
	v_pk_mul_f32 v[40:41], v[40:41], v[192:193] op_sel:[0,1] op_sel_hi:[1,1]
	v_pk_mul_f32 v[42:43], v[42:43], v[192:193] op_sel:[0,1] op_sel_hi:[1,1]
	v_pk_add_f32 v[48:49], v[48:49], 1.0 op_sel_hi:[1,0]
	v_pk_add_f32 v[52:53], v[52:53], 1.0 op_sel_hi:[1,0]
	v_pk_add_f32 v[54:55], v[54:55], 1.0 op_sel_hi:[1,0]
	v_pk_add_f32 v[56:57], v[56:57], 1.0 op_sel_hi:[1,0]
	v_rcp_f32_e32 v48, v48
	v_rcp_f32_e32 v49, v49
	v_rcp_f32_e32 v52, v52
	v_rcp_f32_e32 v53, v53
	v_rcp_f32_e32 v54, v54
	v_rcp_f32_e32 v55, v55
	v_rcp_f32_e32 v56, v56
	v_rcp_f32_e32 v57, v57
	v_pk_mul_f32 v[36:37], v[36:37], v[48:49]
	v_pk_mul_f32 v[38:39], v[38:39], v[52:53]
	v_pk_mul_f32 v[40:41], v[40:41], v[54:55]
	v_pk_mul_f32 v[42:43], v[42:43], v[56:57]
	v_cvt_pk_bf16_f32 v32, v36, v37
	v_cvt_pk_bf16_f32 v33, v38, v39
	v_cvt_pk_bf16_f32 v34, v40, v41
	v_cvt_pk_bf16_f32 v35, v42, v43
	global_store_dwordx4 v[50:51], v[32:35], off
	s_nop 0
	s_waitcnt vmcnt(7)
	v_cvt_f32_u32_e32 v32, v195
	v_cvt_f32_u32_e32 v34, v194
	v_add_u32_e32 v33, 0xa0, v144
	v_fmamk_f32 v32, v34, 0x2f800000, v32
	v_fmamk_f32 v32, v32, 0x3a800000, v158
	v_rsq_f32_e32 v32, v32
	v_mad_i64_i32 v[34:35], s[14:15], v33, s65, v[146:147]
	v_lshl_add_u64 v[34:35], v[34:35], 0, v[148:149]
	v_mul_f32_e32 v194, 0xbfb8aa3b, v32
	v_mul_f32_e32 v195, v32, v32
	v_pk_mul_f32 v[32:33], v[28:29], v[194:195] op_sel_hi:[1,0]
	v_pk_mul_f32 v[36:37], v[30:31], v[194:195] op_sel_hi:[1,0]
	v_pk_mul_f32 v[38:39], v[24:25], v[194:195] op_sel_hi:[1,0]
	v_pk_mul_f32 v[40:41], v[26:27], v[194:195] op_sel_hi:[1,0]
	v_pk_mul_f32 v[20:21], v[20:21], v[28:29]
	v_pk_mul_f32 v[22:23], v[22:23], v[30:31]
	v_pk_mul_f32 v[24:25], v[16:17], v[24:25]
	v_pk_mul_f32 v[26:27], v[18:19], v[26:27]
	v_exp_f32_e32 v32, v32
	v_exp_f32_e32 v33, v33
	v_exp_f32_e32 v36, v36
	v_exp_f32_e32 v37, v37
	v_exp_f32_e32 v38, v38
	v_exp_f32_e32 v39, v39
	v_exp_f32_e32 v40, v40
	v_exp_f32_e32 v41, v41
	v_pk_mul_f32 v[20:21], v[20:21], v[194:195] op_sel:[0,1] op_sel_hi:[1,1]
	v_pk_mul_f32 v[22:23], v[22:23], v[194:195] op_sel:[0,1] op_sel_hi:[1,1]
	v_pk_mul_f32 v[24:25], v[24:25], v[194:195] op_sel:[0,1] op_sel_hi:[1,1]
	v_pk_mul_f32 v[26:27], v[26:27], v[194:195] op_sel:[0,1] op_sel_hi:[1,1]
	v_pk_add_f32 v[32:33], v[32:33], 1.0 op_sel_hi:[1,0]
	v_pk_add_f32 v[36:37], v[36:37], 1.0 op_sel_hi:[1,0]
	v_pk_add_f32 v[38:39], v[38:39], 1.0 op_sel_hi:[1,0]
	v_pk_add_f32 v[40:41], v[40:41], 1.0 op_sel_hi:[1,0]
	v_rcp_f32_e32 v32, v32
	v_rcp_f32_e32 v33, v33
	v_rcp_f32_e32 v36, v36
	v_rcp_f32_e32 v37, v37
	v_rcp_f32_e32 v38, v38
	v_rcp_f32_e32 v39, v39
	v_rcp_f32_e32 v40, v40
	v_rcp_f32_e32 v41, v41
	v_pk_mul_f32 v[20:21], v[20:21], v[32:33]
	v_pk_mul_f32 v[22:23], v[22:23], v[36:37]
	v_pk_mul_f32 v[24:25], v[24:25], v[38:39]
	v_pk_mul_f32 v[26:27], v[26:27], v[40:41]
	v_cvt_pk_bf16_f32 v16, v20, v21
	v_cvt_pk_bf16_f32 v17, v22, v23
	v_cvt_pk_bf16_f32 v18, v24, v25
	v_cvt_pk_bf16_f32 v19, v26, v27
	global_store_dwordx4 v[34:35], v[16:19], off
	s_nop 0
	s_waitcnt vmcnt(7)
	v_cvt_f32_u32_e32 v16, v197
	v_cvt_f32_u32_e32 v18, v196
	v_add_u32_e32 v17, 0xb0, v144
	v_fmamk_f32 v16, v18, 0x2f800000, v16
	v_fmamk_f32 v16, v16, 0x3a800000, v158
	v_rsq_f32_e32 v16, v16
	v_mad_i64_i32 v[18:19], s[14:15], v17, s65, v[146:147]
	v_lshl_add_u64 v[18:19], v[18:19], 0, v[148:149]
	v_mul_f32_e32 v196, 0xbfb8aa3b, v16
	v_mul_f32_e32 v197, v16, v16
	v_pk_mul_f32 v[16:17], v[12:13], v[196:197] op_sel_hi:[1,0]
	v_pk_mul_f32 v[20:21], v[14:15], v[196:197] op_sel_hi:[1,0]
	v_pk_mul_f32 v[22:23], v[8:9], v[196:197] op_sel_hi:[1,0]
	v_pk_mul_f32 v[24:25], v[10:11], v[196:197] op_sel_hi:[1,0]
	v_pk_mul_f32 v[4:5], v[4:5], v[12:13]
	v_pk_mul_f32 v[6:7], v[6:7], v[14:15]
	v_pk_mul_f32 v[8:9], v[0:1], v[8:9]
	v_pk_mul_f32 v[10:11], v[2:3], v[10:11]
	v_exp_f32_e32 v16, v16
	v_exp_f32_e32 v17, v17
	v_exp_f32_e32 v20, v20
	v_exp_f32_e32 v21, v21
	v_exp_f32_e32 v22, v22
	v_exp_f32_e32 v23, v23
	v_exp_f32_e32 v24, v24
	v_exp_f32_e32 v25, v25
	v_pk_mul_f32 v[4:5], v[4:5], v[196:197] op_sel:[0,1] op_sel_hi:[1,1]
	v_pk_mul_f32 v[6:7], v[6:7], v[196:197] op_sel:[0,1] op_sel_hi:[1,1]
	v_pk_mul_f32 v[8:9], v[8:9], v[196:197] op_sel:[0,1] op_sel_hi:[1,1]
	v_pk_mul_f32 v[10:11], v[10:11], v[196:197] op_sel:[0,1] op_sel_hi:[1,1]
	v_pk_add_f32 v[16:17], v[16:17], 1.0 op_sel_hi:[1,0]
	v_pk_add_f32 v[20:21], v[20:21], 1.0 op_sel_hi:[1,0]
	v_pk_add_f32 v[22:23], v[22:23], 1.0 op_sel_hi:[1,0]
	v_pk_add_f32 v[24:25], v[24:25], 1.0 op_sel_hi:[1,0]
	v_rcp_f32_e32 v16, v16
	v_rcp_f32_e32 v17, v17
	v_rcp_f32_e32 v20, v20
	v_rcp_f32_e32 v21, v21
	v_rcp_f32_e32 v22, v22
	v_rcp_f32_e32 v23, v23
	v_rcp_f32_e32 v24, v24
	v_rcp_f32_e32 v25, v25
	v_pk_mul_f32 v[4:5], v[4:5], v[16:17]
	v_pk_mul_f32 v[6:7], v[6:7], v[20:21]
	v_pk_mul_f32 v[8:9], v[8:9], v[22:23]
	v_pk_mul_f32 v[10:11], v[10:11], v[24:25]
	v_cvt_pk_bf16_f32 v0, v4, v5
	v_cvt_pk_bf16_f32 v1, v6, v7
	v_cvt_pk_bf16_f32 v2, v8, v9
	v_cvt_pk_bf16_f32 v3, v10, v11
	global_store_dwordx4 v[18:19], v[0:3], off
	s_cbranch_vccnz .LBB0_187
	s_andn2_b64 vcc, exec, s[8:9]
	s_cbranch_vccnz .LBB0_186
	s_barrier
	s_branch .LBB0_186

; __device__ __forceinline__ float row_rs(const float* ssp, int row) { const unsigned long long v = ((const unsigned long long*)ssp)[row];
;     return __builtin_amdgcn_rsqf((float)v * (1.0f / 4294967296.0f) * (1.0f / 1024.0f) + RMS_EPS); }
; __device__ __forceinline__ void fx_add(float* p, size_t idx, float s) { atomicAdd((unsigned long long*)p + idx, (unsigned long long)(long long)(s * 4294967296.0f)); }
; __device__ __forceinline__ unsigned cvtpk(float lo, float hi) { f32x2v_ v = {lo, hi}; bf16x2v_ b = __builtin_convertvector(v, bf16x2v_); return __builtin_bit_cast(unsigned, b); }
;     __device__ __forceinline__ void operator()(const f32x4 (&acc)[2][2][4][2], const Unit& u, int wr, int wc, int fr, int fq) const {
;         const int row0 = u.pm * BM + wr * 64 + fr, col0 = u.pn * HALF + wc * 32 + 8 * fq;
; #pragma unroll
;         for (int ai = 0; ai < 2; ++ai)
; #pragma unroll
;             for (int m = 0; m < 4; ++m) { const int row = row0 + ai * HALF + m * 16; const float rs = row_rs(ss, row);
;                 float hv[8];
; #pragma unroll
;                 for (int n = 0; n < 2; ++n)
; #pragma unroll
;                     for (int i = 0; i < 4; ++i) { const float g = acc[ai][0][m][n][i] * rs, uu = acc[ai][1][m][n][i] * rs;
;                         hv[n * 4 + i] = g * __builtin_amdgcn_rcpf(1.0f + __expf(-g)) * uu; }
;                 u32x4 w; w.x = cvtpk(hv[0], hv[1]); w.y = cvtpk(hv[2], hv[3]); w.z = cvtpk(hv[4], hv[5]); w.w = cvtpk(hv[6], hv[7]);
;                 *(u32x4*)(H + (size_t)row * ldh + col0) = w; }
.LBB0_960:
	v_lshl_or_b32 v160, s74, 7, v154
	v_ashrrev_i32_e32 v161, 31, v160
	v_or_b32_e32 v164, 16, v144
	v_ashrrev_i32_e32 v165, 31, v164
	v_lshl_add_u64 v[166:167], v[164:165], 3, s[0:1]
	v_mov_b64_e32 v[146:147], s[20:21]
	v_mad_i64_i32 v[162:163], s[54:55], v144, s67, v[146:147]
	s_andn2_b64 vcc, exec, s[10:11]
	s_mov_b64 s[10:11], -1
	s_waitcnt vmcnt(7)
	v_cvt_f32_u32_e32 v159, v183
	v_cvt_f32_u32_e32 v145, v182
	v_lshlrev_b64 v[148:149], 1, v[160:161]
	v_lshl_add_u64 v[162:163], v[162:163], 0, v[148:149]
	v_fmamk_f32 v145, v145, 0x2f800000, v159
	v_fmamk_f32 v145, v145, 0x3a800000, v158
	v_rsq_f32_e32 v160, v145
	s_nop 0
	v_mul_f32_e32 v182, 0xbfb8aa3b, v160
	v_mul_f32_e32 v183, v160, v160
	v_pk_mul_f32 v[160:161], v[124:125], v[182:183] op_sel_hi:[1,0]
	v_pk_mul_f32 v[168:169], v[126:127], v[182:183] op_sel_hi:[1,0]
	v_pk_mul_f32 v[170:171], v[120:121], v[182:183] op_sel_hi:[1,0]
	v_pk_mul_f32 v[172:173], v[122:123], v[182:183] op_sel_hi:[1,0]
	v_pk_mul_f32 v[116:117], v[116:117], v[124:125]
	v_pk_mul_f32 v[118:119], v[118:119], v[126:127]
	v_pk_mul_f32 v[120:121], v[112:113], v[120:121]
	v_pk_mul_f32 v[122:123], v[114:115], v[122:123]
	v_exp_f32_e32 v160, v160
	v_exp_f32_e32 v161, v161
	v_exp_f32_e32 v168, v168
	v_exp_f32_e32 v169, v169
	v_exp_f32_e32 v170, v170
	v_exp_f32_e32 v171, v171
	v_exp_f32_e32 v172, v172
	v_exp_f32_e32 v173, v173
	v_pk_mul_f32 v[116:117], v[116:117], v[182:183] op_sel:[0,1] op_sel_hi:[1,1]
	v_pk_mul_f32 v[118:119], v[118:119], v[182:183] op_sel:[0,1] op_sel_hi:[1,1]
	v_pk_mul_f32 v[120:121], v[120:121], v[182:183] op_sel:[0,1] op_sel_hi:[1,1]
	v_pk_mul_f32 v[122:123], v[122:123], v[182:183] op_sel:[0,1] op_sel_hi:[1,1]
	v_pk_add_f32 v[160:161], v[160:161], 1.0 op_sel_hi:[1,0]
	v_pk_add_f32 v[168:169], v[168:169], 1.0 op_sel_hi:[1,0]
	v_pk_add_f32 v[170:171], v[170:171], 1.0 op_sel_hi:[1,0]
	v_pk_add_f32 v[172:173], v[172:173], 1.0 op_sel_hi:[1,0]
	v_rcp_f32_e32 v160, v160
	v_rcp_f32_e32 v161, v161
	v_rcp_f32_e32 v168, v168
	v_rcp_f32_e32 v169, v169
	v_rcp_f32_e32 v170, v170
	v_rcp_f32_e32 v171, v171
	v_rcp_f32_e32 v172, v172
	v_rcp_f32_e32 v173, v173
	v_pk_mul_f32 v[116:117], v[116:117], v[160:161]
	v_pk_mul_f32 v[118:119], v[118:119], v[168:169]
	v_pk_mul_f32 v[120:121], v[120:121], v[170:171]
	v_pk_mul_f32 v[122:123], v[122:123], v[172:173]
	v_cvt_pk_bf16_f32 v112, v116, v117
	v_cvt_pk_bf16_f32 v113, v118, v119
	v_cvt_pk_bf16_f32 v114, v120, v121
	v_cvt_pk_bf16_f32 v115, v122, v123
	global_store_dwordx4 v[162:163], v[112:115], off
	s_nop 0
	s_nop 0
	v_or_b32_e32 v114, 32, v144
	s_waitcnt vmcnt(7)
	v_cvt_f32_u32_e32 v116, v185
	v_cvt_f32_u32_e32 v115, v184
	v_mad_i64_i32 v[112:113], s[54:55], v164, s67, v[146:147]
	v_fmamk_f32 v115, v115, 0x2f800000, v116
	v_fmamk_f32 v115, v115, 0x3a800000, v158
	v_rsq_f32_e32 v116, v115
	v_ashrrev_i32_e32 v115, 31, v114
	v_lshl_add_u64 v[118:119], v[114:115], 3, s[0:1]
	v_lshl_add_u64 v[112:113], v[112:113], 0, v[148:149]
	v_mul_f32_e32 v184, 0xbfb8aa3b, v116
	v_mul_f32_e32 v185, v116, v116
	v_pk_mul_f32 v[116:117], v[108:109], v[184:185] op_sel_hi:[1,0]
	v_pk_mul_f32 v[120:121], v[110:111], v[184:185] op_sel_hi:[1,0]
	v_pk_mul_f32 v[122:123], v[104:105], v[184:185] op_sel_hi:[1,0]
	v_pk_mul_f32 v[124:125], v[106:107], v[184:185] op_sel_hi:[1,0]
	v_pk_mul_f32 v[100:101], v[100:101], v[108:109]
	v_pk_mul_f32 v[102:103], v[102:103], v[110:111]
	v_pk_mul_f32 v[104:105], v[96:97], v[104:105]
	v_pk_mul_f32 v[106:107], v[98:99], v[106:107]
	v_exp_f32_e32 v116, v116
	v_exp_f32_e32 v117, v117
	v_exp_f32_e32 v120, v120
	v_exp_f32_e32 v121, v121
	v_exp_f32_e32 v122, v122
	v_exp_f32_e32 v123, v123
	v_exp_f32_e32 v124, v124
	v_exp_f32_e32 v125, v125
	v_pk_mul_f32 v[100:101], v[100:101], v[184:185] op_sel:[0,1] op_sel_hi:[1,1]
	v_pk_mul_f32 v[102:103], v[102:103], v[184:185] op_sel:[0,1] op_sel_hi:[1,1]
	v_pk_mul_f32 v[104:105], v[104:105], v[184:185] op_sel:[0,1] op_sel_hi:[1,1]
	v_pk_mul_f32 v[106:107], v[106:107], v[184:185] op_sel:[0,1] op_sel_hi:[1,1]
	v_pk_add_f32 v[116:117], v[116:117], 1.0 op_sel_hi:[1,0]
	v_pk_add_f32 v[120:121], v[120:121], 1.0 op_sel_hi:[1,0]
	v_pk_add_f32 v[122:123], v[122:123], 1.0 op_sel_hi:[1,0]
	v_pk_add_f32 v[124:125], v[124:125], 1.0 op_sel_hi:[1,0]
	v_rcp_f32_e32 v116, v116
	v_rcp_f32_e32 v117, v117
	v_rcp_f32_e32 v120, v120
	v_rcp_f32_e32 v121, v121
	v_rcp_f32_e32 v122, v122
	v_rcp_f32_e32 v123, v123
	v_rcp_f32_e32 v124, v124
	v_rcp_f32_e32 v125, v125
	v_pk_mul_f32 v[100:101], v[100:101], v[116:117]
	v_pk_mul_f32 v[102:103], v[102:103], v[120:121]
	v_pk_mul_f32 v[104:105], v[104:105], v[122:123]
	v_pk_mul_f32 v[106:107], v[106:107], v[124:125]
	v_cvt_pk_bf16_f32 v96, v100, v101
	v_cvt_pk_bf16_f32 v97, v102, v103
	v_cvt_pk_bf16_f32 v98, v104, v105
	v_cvt_pk_bf16_f32 v99, v106, v107
	global_store_dwordx4 v[112:113], v[96:99], off
	s_nop 0
	s_nop 0
	v_or_b32_e32 v98, 48, v144
	s_waitcnt vmcnt(7)
; __device__ __forceinline__ float row_rs(const float* ssp, int row) { const unsigned long long v = ((const unsigned long long*)ssp)[row];
;     return __builtin_amdgcn_rsqf((float)v * (1.0f / 4294967296.0f) * (1.0f / 1024.0f) + RMS_EPS); }
; __device__ __forceinline__ void fx_add(float* p, size_t idx, float s) { atomicAdd((unsigned long long*)p + idx, (unsigned long long)(long long)(s * 4294967296.0f)); }
; __device__ __forceinline__ unsigned cvtpk(float lo, float hi) { f32x2v_ v = {lo, hi}; bf16x2v_ b = __builtin_convertvector(v, bf16x2v_); return __builtin_bit_cast(unsigned, b); }
;     __device__ __forceinline__ void operator()(const f32x4 (&acc)[2][2][4][2], const Unit& u, int wr, int wc, int fr, int fq) const {
;         const int row0 = u.pm * BM + wr * 64 + fr, col0 = u.pn * HALF + wc * 32 + 8 * fq;
; #pragma unroll
;         for (int ai = 0; ai < 2; ++ai)
; #pragma unroll
;             for (int m = 0; m < 4; ++m) { const int row = row0 + ai * HALF + m * 16; const float rs = row_rs(ss, row);
;                 float hv[8];
; #pragma unroll
;                 for (int n = 0; n < 2; ++n)
; #pragma unroll
;                     for (int i = 0; i < 4; ++i) { const float g = acc[ai][0][m][n][i] * rs, uu = acc[ai][1][m][n][i] * rs;
;                         hv[n * 4 + i] = g * __builtin_amdgcn_rcpf(1.0f + __expf(-g)) * uu; }
;                 u32x4 w; w.x = cvtpk(hv[0], hv[1]); w.y = cvtpk(hv[2], hv[3]); w.z = cvtpk(hv[4], hv[5]); w.w = cvtpk(hv[6], hv[7]);
;                 *(u32x4*)(H + (size_t)row * ldh + col0) = w; }
	v_cvt_f32_u32_e32 v100, v187
	v_cvt_f32_u32_e32 v99, v186
	v_mad_i64_i32 v[96:97], s[54:55], v114, s67, v[146:147]
	v_fmamk_f32 v99, v99, 0x2f800000, v100
	v_fmamk_f32 v99, v99, 0x3a800000, v158
	v_rsq_f32_e32 v100, v99
	v_ashrrev_i32_e32 v99, 31, v98
	v_lshl_add_u64 v[102:103], v[98:99], 3, s[0:1]
	v_lshl_add_u64 v[96:97], v[96:97], 0, v[148:149]
	v_mul_f32_e32 v186, 0xbfb8aa3b, v100
	v_mul_f32_e32 v187, v100, v100
	v_pk_mul_f32 v[100:101], v[92:93], v[186:187] op_sel_hi:[1,0]
	v_pk_mul_f32 v[104:105], v[94:95], v[186:187] op_sel_hi:[1,0]
	v_pk_mul_f32 v[106:107], v[88:89], v[186:187] op_sel_hi:[1,0]
	v_pk_mul_f32 v[108:109], v[90:91], v[186:187] op_sel_hi:[1,0]
	v_pk_mul_f32 v[84:85], v[84:85], v[92:93]
	v_pk_mul_f32 v[86:87], v[86:87], v[94:95]
	v_pk_mul_f32 v[88:89], v[80:81], v[88:89]
	v_pk_mul_f32 v[90:91], v[82:83], v[90:91]
	v_exp_f32_e32 v100, v100
	v_exp_f32_e32 v101, v101
	v_exp_f32_e32 v104, v104
	v_exp_f32_e32 v105, v105
	v_exp_f32_e32 v106, v106
	v_exp_f32_e32 v107, v107
	v_exp_f32_e32 v108, v108
	v_exp_f32_e32 v109, v109
	v_pk_mul_f32 v[84:85], v[84:85], v[186:187] op_sel:[0,1] op_sel_hi:[1,1]
	v_pk_mul_f32 v[86:87], v[86:87], v[186:187] op_sel:[0,1] op_sel_hi:[1,1]
	v_pk_mul_f32 v[88:89], v[88:89], v[186:187] op_sel:[0,1] op_sel_hi:[1,1]
	v_pk_mul_f32 v[90:91], v[90:91], v[186:187] op_sel:[0,1] op_sel_hi:[1,1]
	v_pk_add_f32 v[100:101], v[100:101], 1.0 op_sel_hi:[1,0]
	v_pk_add_f32 v[104:105], v[104:105], 1.0 op_sel_hi:[1,0]
	v_pk_add_f32 v[106:107], v[106:107], 1.0 op_sel_hi:[1,0]
	v_pk_add_f32 v[108:109], v[108:109], 1.0 op_sel_hi:[1,0]
	v_rcp_f32_e32 v100, v100
	v_rcp_f32_e32 v101, v101
	v_rcp_f32_e32 v104, v104
	v_rcp_f32_e32 v105, v105
	v_rcp_f32_e32 v106, v106
	v_rcp_f32_e32 v107, v107
	v_rcp_f32_e32 v108, v108
	v_rcp_f32_e32 v109, v109
	v_pk_mul_f32 v[84:85], v[84:85], v[100:101]
	v_pk_mul_f32 v[86:87], v[86:87], v[104:105]
	v_pk_mul_f32 v[88:89], v[88:89], v[106:107]
	v_pk_mul_f32 v[90:91], v[90:91], v[108:109]
	v_cvt_pk_bf16_f32 v80, v84, v85
	v_cvt_pk_bf16_f32 v81, v86, v87
	v_cvt_pk_bf16_f32 v82, v88, v89
	v_cvt_pk_bf16_f32 v83, v90, v91
	global_store_dwordx4 v[96:97], v[80:83], off
	s_nop 0
	s_waitcnt vmcnt(7)
	v_cvt_f32_u32_e32 v80, v189
	v_cvt_f32_u32_e32 v81, v188
	v_mad_i64_i32 v[82:83], s[54:55], v98, s67, v[146:147]
	v_fmamk_f32 v80, v81, 0x2f800000, v80
	v_fmamk_f32 v80, v80, 0x3a800000, v158
	v_rsq_f32_e32 v80, v80
	v_lshl_add_u64 v[82:83], v[82:83], 0, v[148:149]
	v_mul_f32_e32 v188, 0xbfb8aa3b, v80
	v_mul_f32_e32 v189, v80, v80
	v_pk_mul_f32 v[80:81], v[76:77], v[188:189] op_sel_hi:[1,0]
	v_pk_mul_f32 v[84:85], v[78:79], v[188:189] op_sel_hi:[1,0]
	v_pk_mul_f32 v[86:87], v[72:73], v[188:189] op_sel_hi:[1,0]
	v_pk_mul_f32 v[88:89], v[74:75], v[188:189] op_sel_hi:[1,0]
	v_pk_mul_f32 v[68:69], v[68:69], v[76:77]
	v_pk_mul_f32 v[70:71], v[70:71], v[78:79]
	v_pk_mul_f32 v[72:73], v[64:65], v[72:73]
	v_pk_mul_f32 v[74:75], v[66:67], v[74:75]
	v_exp_f32_e32 v80, v80
	v_exp_f32_e32 v81, v81
	v_exp_f32_e32 v84, v84
	v_exp_f32_e32 v85, v85
	v_exp_f32_e32 v86, v86
	v_exp_f32_e32 v87, v87
	v_exp_f32_e32 v88, v88
	v_exp_f32_e32 v89, v89
	v_pk_mul_f32 v[68:69], v[68:69], v[188:189] op_sel:[0,1] op_sel_hi:[1,1]
	v_pk_mul_f32 v[70:71], v[70:71], v[188:189] op_sel:[0,1] op_sel_hi:[1,1]
	v_pk_mul_f32 v[72:73], v[72:73], v[188:189] op_sel:[0,1] op_sel_hi:[1,1]
	v_pk_mul_f32 v[74:75], v[74:75], v[188:189] op_sel:[0,1] op_sel_hi:[1,1]
	v_pk_add_f32 v[80:81], v[80:81], 1.0 op_sel_hi:[1,0]
	v_pk_add_f32 v[84:85], v[84:85], 1.0 op_sel_hi:[1,0]
	v_pk_add_f32 v[86:87], v[86:87], 1.0 op_sel_hi:[1,0]
	v_pk_add_f32 v[88:89], v[88:89], 1.0 op_sel_hi:[1,0]
	v_rcp_f32_e32 v80, v80
	v_rcp_f32_e32 v81, v81
	v_rcp_f32_e32 v84, v84
	v_rcp_f32_e32 v85, v85
	v_rcp_f32_e32 v86, v86
	v_rcp_f32_e32 v87, v87
	v_rcp_f32_e32 v88, v88
	v_rcp_f32_e32 v89, v89
	v_pk_mul_f32 v[68:69], v[68:69], v[80:81]
	v_pk_mul_f32 v[70:71], v[70:71], v[84:85]
	v_pk_mul_f32 v[72:73], v[72:73], v[86:87]
	v_pk_mul_f32 v[74:75], v[74:75], v[88:89]
	v_cvt_pk_bf16_f32 v64, v68, v69
	v_cvt_pk_bf16_f32 v65, v70, v71
	v_cvt_pk_bf16_f32 v66, v72, v73
	v_cvt_pk_bf16_f32 v67, v74, v75
	global_store_dwordx4 v[82:83], v[64:67], off
	s_nop 0
	s_waitcnt vmcnt(7)
	v_cvt_f32_u32_e32 v64, v191
	v_cvt_f32_u32_e32 v66, v190
	v_add_u32_e32 v65, 0x80, v144
	v_fmamk_f32 v64, v66, 0x2f800000, v64
	v_fmamk_f32 v64, v64, 0x3a800000, v158
	v_rsq_f32_e32 v64, v64
	v_mad_i64_i32 v[66:67], s[54:55], v65, s67, v[146:147]
	v_lshl_add_u64 v[66:67], v[66:67], 0, v[148:149]
	v_mul_f32_e32 v190, 0xbfb8aa3b, v64
	v_mul_f32_e32 v191, v64, v64
	v_pk_mul_f32 v[64:65], v[60:61], v[190:191] op_sel_hi:[1,0]
	v_pk_mul_f32 v[68:69], v[62:63], v[190:191] op_sel_hi:[1,0]
	v_pk_mul_f32 v[70:71], v[56:57], v[190:191] op_sel_hi:[1,0]
	v_pk_mul_f32 v[72:73], v[58:59], v[190:191] op_sel_hi:[1,0]
	v_pk_mul_f32 v[52:53], v[52:53], v[60:61]
	v_pk_mul_f32 v[54:55], v[54:55], v[62:63]
	v_pk_mul_f32 v[56:57], v[48:49], v[56:57]
	v_pk_mul_f32 v[58:59], v[50:51], v[58:59]
	v_exp_f32_e32 v64, v64
	v_exp_f32_e32 v65, v65
	v_exp_f32_e32 v68, v68
	v_exp_f32_e32 v69, v69
	v_exp_f32_e32 v70, v70
	v_exp_f32_e32 v71, v71
	v_exp_f32_e32 v72, v72
	v_exp_f32_e32 v73, v73
	v_pk_mul_f32 v[52:53], v[52:53], v[190:191] op_sel:[0,1] op_sel_hi:[1,1]
	v_pk_mul_f32 v[54:55], v[54:55], v[190:191] op_sel:[0,1] op_sel_hi:[1,1]
	v_pk_mul_f32 v[56:57], v[56:57], v[190:191] op_sel:[0,1] op_sel_hi:[1,1]
	v_pk_mul_f32 v[58:59], v[58:59], v[190:191] op_sel:[0,1] op_sel_hi:[1,1]
	v_pk_add_f32 v[64:65], v[64:65], 1.0 op_sel_hi:[1,0]
	v_pk_add_f32 v[68:69], v[68:69], 1.0 op_sel_hi:[1,0]
	v_pk_add_f32 v[70:71], v[70:71], 1.0 op_sel_hi:[1,0]
	v_pk_add_f32 v[72:73], v[72:73], 1.0 op_sel_hi:[1,0]
	v_rcp_f32_e32 v64, v64
	v_rcp_f32_e32 v65, v65
	v_rcp_f32_e32 v68, v68
	v_rcp_f32_e32 v69, v69
	v_rcp_f32_e32 v70, v70
	v_rcp_f32_e32 v71, v71
	v_rcp_f32_e32 v72, v72
	v_rcp_f32_e32 v73, v73
	v_pk_mul_f32 v[52:53], v[52:53], v[64:65]
	v_pk_mul_f32 v[54:55], v[54:55], v[68:69]
	v_pk_mul_f32 v[56:57], v[56:57], v[70:71]
	v_pk_mul_f32 v[58:59], v[58:59], v[72:73]
	v_cvt_pk_bf16_f32 v48, v52, v53
	v_cvt_pk_bf16_f32 v49, v54, v55
	v_cvt_pk_bf16_f32 v50, v56, v57
	v_cvt_pk_bf16_f32 v51, v58, v59
	global_store_dwordx4 v[66:67], v[48:51], off
	s_nop 0
	s_waitcnt vmcnt(7)
; __device__ __forceinline__ unsigned cvtpk(float lo, float hi) { f32x2v_ v = {lo, hi}; bf16x2v_ b = __builtin_convertvector(v, bf16x2v_); return __builtin_bit_cast(unsigned, b); }
; #define PG8_BAR __builtin_amdgcn_s_barrier()
;     __device__ __forceinline__ void operator()(const f32x4 (&acc)[2][2][4][2], const Unit& u, int wr, int wc, int fr, int fq) const {
;     ...
;             for (int m = 0; m < 4; ++m) { const int row = row0 + ai * HALF + m * 16; const float rs = row_rs(ss, row);
;                 float hv[8];
; #pragma unroll
;                 for (int n = 0; n < 2; ++n)
; #pragma unroll
;                     for (int i = 0; i < 4; ++i) { const float g = acc[ai][0][m][n][i] * rs, uu = acc[ai][1][m][n][i] * rs;
;                         hv[n * 4 + i] = g * __builtin_amdgcn_rcpf(1.0f + __expf(-g)) * uu; }
;                 u32x4 w; w.x = cvtpk(hv[0], hv[1]); w.y = cvtpk(hv[2], hv[3]); w.z = cvtpk(hv[4], hv[5]); w.w = cvtpk(hv[6], hv[7]);
;                 *(u32x4*)(H + (size_t)row * ldh + col0) = w; }
; template <class Epi, class Sched, bool ALIGN_EPI = false, bool SP2 = false>
; __device__ __forceinline__ void gemm_phase(PG8_LAS unsigned char* lds, const Gemm g, const Sched& S, const Epi& E) {
;     ...
;         if (!has_next) break;
; #pragma unroll
;         for (int a = 0; a < 2; ++a)
; #pragma unroll
;             for (int b = 0; b < 2; ++b)
; #pragma unroll
;                 for (int m = 0; m < 4; ++m)
; #pragma unroll
;                     for (int n = 0; n < 2; ++n) acc[a][b][m][n] = (f32x4){0.f, 0.f, 0.f, 0.f};
;         cur = nxt; cA = nA; cB = nB; ++ui;
;         if constexpr (ALIGN_EPI) { if (wr == 1) PG8_BAR; }
	v_cvt_f32_u32_e32 v48, v193
	v_cvt_f32_u32_e32 v50, v192
	v_add_u32_e32 v49, 0x90, v144
	v_fmamk_f32 v48, v50, 0x2f800000, v48
	v_fmamk_f32 v48, v48, 0x3a800000, v158
	v_rsq_f32_e32 v48, v48
	v_mad_i64_i32 v[50:51], s[54:55], v49, s67, v[146:147]
	v_lshl_add_u64 v[50:51], v[50:51], 0, v[148:149]
	v_mul_f32_e32 v192, 0xbfb8aa3b, v48
	v_mul_f32_e32 v193, v48, v48
	v_pk_mul_f32 v[48:49], v[44:45], v[192:193] op_sel_hi:[1,0]
	v_pk_mul_f32 v[52:53], v[46:47], v[192:193] op_sel_hi:[1,0]
	v_pk_mul_f32 v[54:55], v[40:41], v[192:193] op_sel_hi:[1,0]
	v_pk_mul_f32 v[56:57], v[42:43], v[192:193] op_sel_hi:[1,0]
	v_pk_mul_f32 v[36:37], v[36:37], v[44:45]
	v_pk_mul_f32 v[38:39], v[38:39], v[46:47]
	v_pk_mul_f32 v[40:41], v[32:33], v[40:41]
	v_pk_mul_f32 v[42:43], v[34:35], v[42:43]
	v_exp_f32_e32 v48, v48
	v_exp_f32_e32 v49, v49
	v_exp_f32_e32 v52, v52
	v_exp_f32_e32 v53, v53
	v_exp_f32_e32 v54, v54
	v_exp_f32_e32 v55, v55
	v_exp_f32_e32 v56, v56
	v_exp_f32_e32 v57, v57
	v_pk_mul_f32 v[36:37], v[36:37], v[192:193] op_sel:[0,1] op_sel_hi:[1,1]
	v_pk_mul_f32 v[38:39], v[38:39], v[192:193] op_sel:[0,1] op_sel_hi:[1,1]
	v_pk_mul_f32 v[40:41], v[40:41], v[192:193] op_sel:[0,1] op_sel_hi:[1,1]
	v_pk_mul_f32 v[42:43], v[42:43], v[192:193] op_sel:[0,1] op_sel_hi:[1,1]
	v_pk_add_f32 v[48:49], v[48:49], 1.0 op_sel_hi:[1,0]
	v_pk_add_f32 v[52:53], v[52:53], 1.0 op_sel_hi:[1,0]
	v_pk_add_f32 v[54:55], v[54:55], 1.0 op_sel_hi:[1,0]
	v_pk_add_f32 v[56:57], v[56:57], 1.0 op_sel_hi:[1,0]
	v_rcp_f32_e32 v48, v48
	v_rcp_f32_e32 v49, v49
	v_rcp_f32_e32 v52, v52
	v_rcp_f32_e32 v53, v53
	v_rcp_f32_e32 v54, v54
	v_rcp_f32_e32 v55, v55
	v_rcp_f32_e32 v56, v56
	v_rcp_f32_e32 v57, v57
	v_pk_mul_f32 v[36:37], v[36:37], v[48:49]
	v_pk_mul_f32 v[38:39], v[38:39], v[52:53]
	v_pk_mul_f32 v[40:41], v[40:41], v[54:55]
	v_pk_mul_f32 v[42:43], v[42:43], v[56:57]
	v_cvt_pk_bf16_f32 v32, v36, v37
	v_cvt_pk_bf16_f32 v33, v38, v39
	v_cvt_pk_bf16_f32 v34, v40, v41
	v_cvt_pk_bf16_f32 v35, v42, v43
	global_store_dwordx4 v[50:51], v[32:35], off
	s_nop 0
	s_waitcnt vmcnt(7)
	v_cvt_f32_u32_e32 v32, v195
	v_cvt_f32_u32_e32 v34, v194
	v_add_u32_e32 v33, 0xa0, v144
	v_fmamk_f32 v32, v34, 0x2f800000, v32
	v_fmamk_f32 v32, v32, 0x3a800000, v158
	v_rsq_f32_e32 v32, v32
	v_mad_i64_i32 v[34:35], s[54:55], v33, s67, v[146:147]
	v_lshl_add_u64 v[34:35], v[34:35], 0, v[148:149]
	v_mul_f32_e32 v194, 0xbfb8aa3b, v32
	v_mul_f32_e32 v195, v32, v32
	v_pk_mul_f32 v[32:33], v[28:29], v[194:195] op_sel_hi:[1,0]
	v_pk_mul_f32 v[36:37], v[30:31], v[194:195] op_sel_hi:[1,0]
	v_pk_mul_f32 v[38:39], v[24:25], v[194:195] op_sel_hi:[1,0]
	v_pk_mul_f32 v[40:41], v[26:27], v[194:195] op_sel_hi:[1,0]
	v_pk_mul_f32 v[20:21], v[20:21], v[28:29]
	v_pk_mul_f32 v[22:23], v[22:23], v[30:31]
	v_pk_mul_f32 v[24:25], v[16:17], v[24:25]
	v_pk_mul_f32 v[26:27], v[18:19], v[26:27]
	v_exp_f32_e32 v32, v32
	v_exp_f32_e32 v33, v33
	v_exp_f32_e32 v36, v36
	v_exp_f32_e32 v37, v37
	v_exp_f32_e32 v38, v38
	v_exp_f32_e32 v39, v39
	v_exp_f32_e32 v40, v40
	v_exp_f32_e32 v41, v41
	v_pk_mul_f32 v[20:21], v[20:21], v[194:195] op_sel:[0,1] op_sel_hi:[1,1]
	v_pk_mul_f32 v[22:23], v[22:23], v[194:195] op_sel:[0,1] op_sel_hi:[1,1]
	v_pk_mul_f32 v[24:25], v[24:25], v[194:195] op_sel:[0,1] op_sel_hi:[1,1]
	v_pk_mul_f32 v[26:27], v[26:27], v[194:195] op_sel:[0,1] op_sel_hi:[1,1]
	v_pk_add_f32 v[32:33], v[32:33], 1.0 op_sel_hi:[1,0]
	v_pk_add_f32 v[36:37], v[36:37], 1.0 op_sel_hi:[1,0]
	v_pk_add_f32 v[38:39], v[38:39], 1.0 op_sel_hi:[1,0]
	v_pk_add_f32 v[40:41], v[40:41], 1.0 op_sel_hi:[1,0]
	v_rcp_f32_e32 v32, v32
	v_rcp_f32_e32 v33, v33
	v_rcp_f32_e32 v36, v36
	v_rcp_f32_e32 v37, v37
	v_rcp_f32_e32 v38, v38
	v_rcp_f32_e32 v39, v39
	v_rcp_f32_e32 v40, v40
	v_rcp_f32_e32 v41, v41
	v_pk_mul_f32 v[20:21], v[20:21], v[32:33]
	v_pk_mul_f32 v[22:23], v[22:23], v[36:37]
	v_pk_mul_f32 v[24:25], v[24:25], v[38:39]
	v_pk_mul_f32 v[26:27], v[26:27], v[40:41]
	v_cvt_pk_bf16_f32 v16, v20, v21
	v_cvt_pk_bf16_f32 v17, v22, v23
	v_cvt_pk_bf16_f32 v18, v24, v25
	v_cvt_pk_bf16_f32 v19, v26, v27
	global_store_dwordx4 v[34:35], v[16:19], off
	s_nop 0
	s_waitcnt vmcnt(7)
	v_cvt_f32_u32_e32 v16, v197
	v_cvt_f32_u32_e32 v18, v196
	v_add_u32_e32 v17, 0xb0, v144
	v_fmamk_f32 v16, v18, 0x2f800000, v16
	v_fmamk_f32 v16, v16, 0x3a800000, v158
	v_rsq_f32_e32 v16, v16
	v_mad_i64_i32 v[18:19], s[54:55], v17, s67, v[146:147]
	v_lshl_add_u64 v[18:19], v[18:19], 0, v[148:149]
	v_mul_f32_e32 v196, 0xbfb8aa3b, v16
	v_mul_f32_e32 v197, v16, v16
	v_pk_mul_f32 v[16:17], v[12:13], v[196:197] op_sel_hi:[1,0]
	v_pk_mul_f32 v[20:21], v[14:15], v[196:197] op_sel_hi:[1,0]
	v_pk_mul_f32 v[22:23], v[8:9], v[196:197] op_sel_hi:[1,0]
	v_pk_mul_f32 v[24:25], v[10:11], v[196:197] op_sel_hi:[1,0]
	v_pk_mul_f32 v[4:5], v[4:5], v[12:13]
	v_pk_mul_f32 v[6:7], v[6:7], v[14:15]
	v_pk_mul_f32 v[8:9], v[0:1], v[8:9]
	v_pk_mul_f32 v[10:11], v[2:3], v[10:11]
	v_exp_f32_e32 v16, v16
	v_exp_f32_e32 v17, v17
	v_exp_f32_e32 v20, v20
	v_exp_f32_e32 v21, v21
	v_exp_f32_e32 v22, v22
	v_exp_f32_e32 v23, v23
	v_exp_f32_e32 v24, v24
	v_exp_f32_e32 v25, v25
	v_pk_mul_f32 v[4:5], v[4:5], v[196:197] op_sel:[0,1] op_sel_hi:[1,1]
	v_pk_mul_f32 v[6:7], v[6:7], v[196:197] op_sel:[0,1] op_sel_hi:[1,1]
	v_pk_mul_f32 v[8:9], v[8:9], v[196:197] op_sel:[0,1] op_sel_hi:[1,1]
	v_pk_mul_f32 v[10:11], v[10:11], v[196:197] op_sel:[0,1] op_sel_hi:[1,1]
	v_pk_add_f32 v[16:17], v[16:17], 1.0 op_sel_hi:[1,0]
	v_pk_add_f32 v[20:21], v[20:21], 1.0 op_sel_hi:[1,0]
	v_pk_add_f32 v[22:23], v[22:23], 1.0 op_sel_hi:[1,0]
	v_pk_add_f32 v[24:25], v[24:25], 1.0 op_sel_hi:[1,0]
	v_rcp_f32_e32 v16, v16
	v_rcp_f32_e32 v17, v17
	v_rcp_f32_e32 v20, v20
	v_rcp_f32_e32 v21, v21
	v_rcp_f32_e32 v22, v22
	v_rcp_f32_e32 v23, v23
	v_rcp_f32_e32 v24, v24
	v_rcp_f32_e32 v25, v25
	v_pk_mul_f32 v[4:5], v[4:5], v[16:17]
	v_pk_mul_f32 v[6:7], v[6:7], v[20:21]
	v_pk_mul_f32 v[8:9], v[8:9], v[22:23]
	v_pk_mul_f32 v[10:11], v[10:11], v[24:25]
	v_cvt_pk_bf16_f32 v0, v4, v5
	v_cvt_pk_bf16_f32 v1, v6, v7
	v_cvt_pk_bf16_f32 v2, v8, v9
	v_cvt_pk_bf16_f32 v3, v10, v11
	global_store_dwordx4 v[18:19], v[0:3], off
	s_cbranch_vccnz .LBB0_953
	s_andn2_b64 vcc, exec, s[12:13]
	s_cbranch_vccnz .LBB0_952
	s_barrier
	s_branch .LBB0_952

; __device__ __forceinline__ float row_rs(const float* ssp, int row) { const unsigned long long v = ((const unsigned long long*)ssp)[row];
;     return __builtin_amdgcn_rsqf((float)v * (1.0f / 4294967296.0f) * (1.0f / 1024.0f) + RMS_EPS); }
; __device__ __forceinline__ void fx_add(float* p, size_t idx, float s) { atomicAdd((unsigned long long*)p + idx, (unsigned long long)(long long)(s * 4294967296.0f)); }
; __device__ __forceinline__ unsigned cvtpk(float lo, float hi) { f32x2v_ v = {lo, hi}; bf16x2v_ b = __builtin_convertvector(v, bf16x2v_); return __builtin_bit_cast(unsigned, b); }
;     __device__ __forceinline__ void operator()(const f32x4 (&acc)[2][2][4][2], const Unit& u, int wr, int wc, int fr, int fq) const {
;         const int row0 = u.pm * BM + wr * 64 + fr, col0 = u.pn * HALF + wc * 32 + 8 * fq;
; #pragma unroll
;         for (int ai = 0; ai < 2; ++ai)
; #pragma unroll
;             for (int m = 0; m < 4; ++m) { const int row = row0 + ai * HALF + m * 16; const float rs = row_rs(ss, row);
;                 float hv[8];
; #pragma unroll
;                 for (int n = 0; n < 2; ++n)
; #pragma unroll
;                     for (int i = 0; i < 4; ++i) { const float g = acc[ai][0][m][n][i] * rs, uu = acc[ai][1][m][n][i] * rs;
;                         hv[n * 4 + i] = g * __builtin_amdgcn_rcpf(1.0f + __expf(-g)) * uu; }
;                 u32x4 w; w.x = cvtpk(hv[0], hv[1]); w.y = cvtpk(hv[2], hv[3]); w.z = cvtpk(hv[4], hv[5]); w.w = cvtpk(hv[6], hv[7]);
;                 *(u32x4*)(H + (size_t)row * ldh + col0) = w; }
.LBB0_1122:
	v_lshl_or_b32 v160, s75, 7, v154
	v_ashrrev_i32_e32 v161, 31, v160
	v_or_b32_e32 v164, 16, v144
	v_ashrrev_i32_e32 v165, 31, v164
	v_lshl_add_u64 v[166:167], v[164:165], 3, s[36:37]
	v_mov_b64_e32 v[146:147], s[20:21]
	v_mad_i64_i32 v[162:163], s[54:55], v144, s74, v[146:147]
	s_andn2_b64 vcc, exec, s[10:11]
	s_mov_b64 s[10:11], -1
	s_waitcnt vmcnt(7)
	v_cvt_f32_u32_e32 v159, v183
	v_cvt_f32_u32_e32 v145, v182
	v_lshlrev_b64 v[148:149], 1, v[160:161]
	v_lshl_add_u64 v[162:163], v[162:163], 0, v[148:149]
	v_fmamk_f32 v145, v145, 0x2f800000, v159
	v_fmamk_f32 v145, v145, 0x3a800000, v158
	v_rsq_f32_e32 v160, v145
	s_nop 0
	v_mul_f32_e32 v182, 0xbfb8aa3b, v160
	v_mul_f32_e32 v183, v160, v160
	v_pk_mul_f32 v[160:161], v[124:125], v[182:183] op_sel_hi:[1,0]
	v_pk_mul_f32 v[168:169], v[126:127], v[182:183] op_sel_hi:[1,0]
	v_pk_mul_f32 v[170:171], v[120:121], v[182:183] op_sel_hi:[1,0]
	v_pk_mul_f32 v[172:173], v[122:123], v[182:183] op_sel_hi:[1,0]
	v_pk_mul_f32 v[116:117], v[116:117], v[124:125]
	v_pk_mul_f32 v[118:119], v[118:119], v[126:127]
	v_pk_mul_f32 v[120:121], v[112:113], v[120:121]
	v_pk_mul_f32 v[122:123], v[114:115], v[122:123]
	v_exp_f32_e32 v160, v160
	v_exp_f32_e32 v161, v161
	v_exp_f32_e32 v168, v168
	v_exp_f32_e32 v169, v169
	v_exp_f32_e32 v170, v170
	v_exp_f32_e32 v171, v171
	v_exp_f32_e32 v172, v172
	v_exp_f32_e32 v173, v173
	v_pk_mul_f32 v[116:117], v[116:117], v[182:183] op_sel:[0,1] op_sel_hi:[1,1]
	v_pk_mul_f32 v[118:119], v[118:119], v[182:183] op_sel:[0,1] op_sel_hi:[1,1]
	v_pk_mul_f32 v[120:121], v[120:121], v[182:183] op_sel:[0,1] op_sel_hi:[1,1]
	v_pk_mul_f32 v[122:123], v[122:123], v[182:183] op_sel:[0,1] op_sel_hi:[1,1]
	v_pk_add_f32 v[160:161], v[160:161], 1.0 op_sel_hi:[1,0]
	v_pk_add_f32 v[168:169], v[168:169], 1.0 op_sel_hi:[1,0]
	v_pk_add_f32 v[170:171], v[170:171], 1.0 op_sel_hi:[1,0]
	v_pk_add_f32 v[172:173], v[172:173], 1.0 op_sel_hi:[1,0]
	v_rcp_f32_e32 v160, v160
	v_rcp_f32_e32 v161, v161
	v_rcp_f32_e32 v168, v168
	v_rcp_f32_e32 v169, v169
	v_rcp_f32_e32 v170, v170
	v_rcp_f32_e32 v171, v171
	v_rcp_f32_e32 v172, v172
	v_rcp_f32_e32 v173, v173
	v_pk_mul_f32 v[116:117], v[116:117], v[160:161]
	v_pk_mul_f32 v[118:119], v[118:119], v[168:169]
	v_pk_mul_f32 v[120:121], v[120:121], v[170:171]
	v_pk_mul_f32 v[122:123], v[122:123], v[172:173]
	v_cvt_pk_bf16_f32 v112, v116, v117
	v_cvt_pk_bf16_f32 v113, v118, v119
	v_cvt_pk_bf16_f32 v114, v120, v121
	v_cvt_pk_bf16_f32 v115, v122, v123
	global_store_dwordx4 v[162:163], v[112:115], off
	s_nop 0
	s_nop 0
	v_or_b32_e32 v114, 32, v144
	s_waitcnt vmcnt(7)
	v_cvt_f32_u32_e32 v116, v185
	v_cvt_f32_u32_e32 v115, v184
	v_mad_i64_i32 v[112:113], s[54:55], v164, s74, v[146:147]
	v_fmamk_f32 v115, v115, 0x2f800000, v116
	v_fmamk_f32 v115, v115, 0x3a800000, v158
	v_rsq_f32_e32 v116, v115
	v_ashrrev_i32_e32 v115, 31, v114
	v_lshl_add_u64 v[118:119], v[114:115], 3, s[36:37]
	v_lshl_add_u64 v[112:113], v[112:113], 0, v[148:149]
	v_mul_f32_e32 v184, 0xbfb8aa3b, v116
	v_mul_f32_e32 v185, v116, v116
	v_pk_mul_f32 v[116:117], v[108:109], v[184:185] op_sel_hi:[1,0]
	v_pk_mul_f32 v[120:121], v[110:111], v[184:185] op_sel_hi:[1,0]
	v_pk_mul_f32 v[122:123], v[104:105], v[184:185] op_sel_hi:[1,0]
	v_pk_mul_f32 v[124:125], v[106:107], v[184:185] op_sel_hi:[1,0]
	v_pk_mul_f32 v[100:101], v[100:101], v[108:109]
	v_pk_mul_f32 v[102:103], v[102:103], v[110:111]
	v_pk_mul_f32 v[104:105], v[96:97], v[104:105]
	v_pk_mul_f32 v[106:107], v[98:99], v[106:107]
	v_exp_f32_e32 v116, v116
	v_exp_f32_e32 v117, v117
	v_exp_f32_e32 v120, v120
	v_exp_f32_e32 v121, v121
	v_exp_f32_e32 v122, v122
	v_exp_f32_e32 v123, v123
	v_exp_f32_e32 v124, v124
	v_exp_f32_e32 v125, v125
	v_pk_mul_f32 v[100:101], v[100:101], v[184:185] op_sel:[0,1] op_sel_hi:[1,1]
	v_pk_mul_f32 v[102:103], v[102:103], v[184:185] op_sel:[0,1] op_sel_hi:[1,1]
	v_pk_mul_f32 v[104:105], v[104:105], v[184:185] op_sel:[0,1] op_sel_hi:[1,1]
	v_pk_mul_f32 v[106:107], v[106:107], v[184:185] op_sel:[0,1] op_sel_hi:[1,1]
	v_pk_add_f32 v[116:117], v[116:117], 1.0 op_sel_hi:[1,0]
	v_pk_add_f32 v[120:121], v[120:121], 1.0 op_sel_hi:[1,0]
	v_pk_add_f32 v[122:123], v[122:123], 1.0 op_sel_hi:[1,0]
	v_pk_add_f32 v[124:125], v[124:125], 1.0 op_sel_hi:[1,0]
	v_rcp_f32_e32 v116, v116
	v_rcp_f32_e32 v117, v117
	v_rcp_f32_e32 v120, v120
	v_rcp_f32_e32 v121, v121
	v_rcp_f32_e32 v122, v122
	v_rcp_f32_e32 v123, v123
	v_rcp_f32_e32 v124, v124
	v_rcp_f32_e32 v125, v125
	v_pk_mul_f32 v[100:101], v[100:101], v[116:117]
	v_pk_mul_f32 v[102:103], v[102:103], v[120:121]
	v_pk_mul_f32 v[104:105], v[104:105], v[122:123]
	v_pk_mul_f32 v[106:107], v[106:107], v[124:125]
	v_cvt_pk_bf16_f32 v96, v100, v101
	v_cvt_pk_bf16_f32 v97, v102, v103
	v_cvt_pk_bf16_f32 v98, v104, v105
	v_cvt_pk_bf16_f32 v99, v106, v107
	global_store_dwordx4 v[112:113], v[96:99], off
	s_nop 0
	s_nop 0
	v_or_b32_e32 v98, 48, v144
	s_waitcnt vmcnt(7)
; __device__ __forceinline__ float row_rs(const float* ssp, int row) { const unsigned long long v = ((const unsigned long long*)ssp)[row];
;     return __builtin_amdgcn_rsqf((float)v * (1.0f / 4294967296.0f) * (1.0f / 1024.0f) + RMS_EPS); }
; __device__ __forceinline__ void fx_add(float* p, size_t idx, float s) { atomicAdd((unsigned long long*)p + idx, (unsigned long long)(long long)(s * 4294967296.0f)); }
; __device__ __forceinline__ unsigned cvtpk(float lo, float hi) { f32x2v_ v = {lo, hi}; bf16x2v_ b = __builtin_convertvector(v, bf16x2v_); return __builtin_bit_cast(unsigned, b); }
;     __device__ __forceinline__ void operator()(const f32x4 (&acc)[2][2][4][2], const Unit& u, int wr, int wc, int fr, int fq) const {
;         const int row0 = u.pm * BM + wr * 64 + fr, col0 = u.pn * HALF + wc * 32 + 8 * fq;
; #pragma unroll
;         for (int ai = 0; ai < 2; ++ai)
; #pragma unroll
;             for (int m = 0; m < 4; ++m) { const int row = row0 + ai * HALF + m * 16; const float rs = row_rs(ss, row);
;                 float hv[8];
; #pragma unroll
;                 for (int n = 0; n < 2; ++n)
; #pragma unroll
;                     for (int i = 0; i < 4; ++i) { const float g = acc[ai][0][m][n][i] * rs, uu = acc[ai][1][m][n][i] * rs;
;                         hv[n * 4 + i] = g * __builtin_amdgcn_rcpf(1.0f + __expf(-g)) * uu; }
;                 u32x4 w; w.x = cvtpk(hv[0], hv[1]); w.y = cvtpk(hv[2], hv[3]); w.z = cvtpk(hv[4], hv[5]); w.w = cvtpk(hv[6], hv[7]);
;                 *(u32x4*)(H + (size_t)row * ldh + col0) = w; }
	v_cvt_f32_u32_e32 v100, v187
	v_cvt_f32_u32_e32 v99, v186
	v_mad_i64_i32 v[96:97], s[54:55], v114, s74, v[146:147]
	v_fmamk_f32 v99, v99, 0x2f800000, v100
	v_fmamk_f32 v99, v99, 0x3a800000, v158
	v_rsq_f32_e32 v100, v99
	v_ashrrev_i32_e32 v99, 31, v98
	v_lshl_add_u64 v[102:103], v[98:99], 3, s[36:37]
	v_lshl_add_u64 v[96:97], v[96:97], 0, v[148:149]
	v_mul_f32_e32 v186, 0xbfb8aa3b, v100
	v_mul_f32_e32 v187, v100, v100
	v_pk_mul_f32 v[100:101], v[92:93], v[186:187] op_sel_hi:[1,0]
	v_pk_mul_f32 v[104:105], v[94:95], v[186:187] op_sel_hi:[1,0]
	v_pk_mul_f32 v[106:107], v[88:89], v[186:187] op_sel_hi:[1,0]
	v_pk_mul_f32 v[108:109], v[90:91], v[186:187] op_sel_hi:[1,0]
	v_pk_mul_f32 v[84:85], v[84:85], v[92:93]
	v_pk_mul_f32 v[86:87], v[86:87], v[94:95]
	v_pk_mul_f32 v[88:89], v[80:81], v[88:89]
	v_pk_mul_f32 v[90:91], v[82:83], v[90:91]
	v_exp_f32_e32 v100, v100
	v_exp_f32_e32 v101, v101
	v_exp_f32_e32 v104, v104
	v_exp_f32_e32 v105, v105
	v_exp_f32_e32 v106, v106
	v_exp_f32_e32 v107, v107
	v_exp_f32_e32 v108, v108
	v_exp_f32_e32 v109, v109
	v_pk_mul_f32 v[84:85], v[84:85], v[186:187] op_sel:[0,1] op_sel_hi:[1,1]
	v_pk_mul_f32 v[86:87], v[86:87], v[186:187] op_sel:[0,1] op_sel_hi:[1,1]
	v_pk_mul_f32 v[88:89], v[88:89], v[186:187] op_sel:[0,1] op_sel_hi:[1,1]
	v_pk_mul_f32 v[90:91], v[90:91], v[186:187] op_sel:[0,1] op_sel_hi:[1,1]
	v_pk_add_f32 v[100:101], v[100:101], 1.0 op_sel_hi:[1,0]
	v_pk_add_f32 v[104:105], v[104:105], 1.0 op_sel_hi:[1,0]
	v_pk_add_f32 v[106:107], v[106:107], 1.0 op_sel_hi:[1,0]
	v_pk_add_f32 v[108:109], v[108:109], 1.0 op_sel_hi:[1,0]
	v_rcp_f32_e32 v100, v100
	v_rcp_f32_e32 v101, v101
	v_rcp_f32_e32 v104, v104
	v_rcp_f32_e32 v105, v105
	v_rcp_f32_e32 v106, v106
	v_rcp_f32_e32 v107, v107
	v_rcp_f32_e32 v108, v108
	v_rcp_f32_e32 v109, v109
	v_pk_mul_f32 v[84:85], v[84:85], v[100:101]
	v_pk_mul_f32 v[86:87], v[86:87], v[104:105]
	v_pk_mul_f32 v[88:89], v[88:89], v[106:107]
	v_pk_mul_f32 v[90:91], v[90:91], v[108:109]
	v_cvt_pk_bf16_f32 v80, v84, v85
	v_cvt_pk_bf16_f32 v81, v86, v87
	v_cvt_pk_bf16_f32 v82, v88, v89
	v_cvt_pk_bf16_f32 v83, v90, v91
	global_store_dwordx4 v[96:97], v[80:83], off
	s_nop 0
	s_waitcnt vmcnt(7)
	v_cvt_f32_u32_e32 v80, v189
	v_cvt_f32_u32_e32 v81, v188
	v_mad_i64_i32 v[82:83], s[54:55], v98, s74, v[146:147]
	v_fmamk_f32 v80, v81, 0x2f800000, v80
	v_fmamk_f32 v80, v80, 0x3a800000, v158
	v_rsq_f32_e32 v80, v80
	v_lshl_add_u64 v[82:83], v[82:83], 0, v[148:149]
	v_mul_f32_e32 v188, 0xbfb8aa3b, v80
	v_mul_f32_e32 v189, v80, v80
	v_pk_mul_f32 v[80:81], v[76:77], v[188:189] op_sel_hi:[1,0]
	v_pk_mul_f32 v[84:85], v[78:79], v[188:189] op_sel_hi:[1,0]
	v_pk_mul_f32 v[86:87], v[72:73], v[188:189] op_sel_hi:[1,0]
	v_pk_mul_f32 v[88:89], v[74:75], v[188:189] op_sel_hi:[1,0]
	v_pk_mul_f32 v[68:69], v[68:69], v[76:77]
	v_pk_mul_f32 v[70:71], v[70:71], v[78:79]
	v_pk_mul_f32 v[72:73], v[64:65], v[72:73]
	v_pk_mul_f32 v[74:75], v[66:67], v[74:75]
	v_exp_f32_e32 v80, v80
	v_exp_f32_e32 v81, v81
	v_exp_f32_e32 v84, v84
	v_exp_f32_e32 v85, v85
	v_exp_f32_e32 v86, v86
	v_exp_f32_e32 v87, v87
	v_exp_f32_e32 v88, v88
	v_exp_f32_e32 v89, v89
	v_pk_mul_f32 v[68:69], v[68:69], v[188:189] op_sel:[0,1] op_sel_hi:[1,1]
	v_pk_mul_f32 v[70:71], v[70:71], v[188:189] op_sel:[0,1] op_sel_hi:[1,1]
	v_pk_mul_f32 v[72:73], v[72:73], v[188:189] op_sel:[0,1] op_sel_hi:[1,1]
	v_pk_mul_f32 v[74:75], v[74:75], v[188:189] op_sel:[0,1] op_sel_hi:[1,1]
	v_pk_add_f32 v[80:81], v[80:81], 1.0 op_sel_hi:[1,0]
	v_pk_add_f32 v[84:85], v[84:85], 1.0 op_sel_hi:[1,0]
	v_pk_add_f32 v[86:87], v[86:87], 1.0 op_sel_hi:[1,0]
	v_pk_add_f32 v[88:89], v[88:89], 1.0 op_sel_hi:[1,0]
	v_rcp_f32_e32 v80, v80
	v_rcp_f32_e32 v81, v81
	v_rcp_f32_e32 v84, v84
	v_rcp_f32_e32 v85, v85
	v_rcp_f32_e32 v86, v86
	v_rcp_f32_e32 v87, v87
	v_rcp_f32_e32 v88, v88
	v_rcp_f32_e32 v89, v89
	v_pk_mul_f32 v[68:69], v[68:69], v[80:81]
	v_pk_mul_f32 v[70:71], v[70:71], v[84:85]
	v_pk_mul_f32 v[72:73], v[72:73], v[86:87]
	v_pk_mul_f32 v[74:75], v[74:75], v[88:89]
	v_cvt_pk_bf16_f32 v64, v68, v69
	v_cvt_pk_bf16_f32 v65, v70, v71
	v_cvt_pk_bf16_f32 v66, v72, v73
	v_cvt_pk_bf16_f32 v67, v74, v75
	global_store_dwordx4 v[82:83], v[64:67], off
	s_nop 0
	s_waitcnt vmcnt(7)
	v_cvt_f32_u32_e32 v64, v191
	v_cvt_f32_u32_e32 v66, v190
	v_add_u32_e32 v65, 0x80, v144
	v_fmamk_f32 v64, v66, 0x2f800000, v64
	v_fmamk_f32 v64, v64, 0x3a800000, v158
	v_rsq_f32_e32 v64, v64
	v_mad_i64_i32 v[66:67], s[54:55], v65, s74, v[146:147]
	v_lshl_add_u64 v[66:67], v[66:67], 0, v[148:149]
	v_mul_f32_e32 v190, 0xbfb8aa3b, v64
	v_mul_f32_e32 v191, v64, v64
	v_pk_mul_f32 v[64:65], v[60:61], v[190:191] op_sel_hi:[1,0]
	v_pk_mul_f32 v[68:69], v[62:63], v[190:191] op_sel_hi:[1,0]
	v_pk_mul_f32 v[70:71], v[56:57], v[190:191] op_sel_hi:[1,0]
	v_pk_mul_f32 v[72:73], v[58:59], v[190:191] op_sel_hi:[1,0]
	v_pk_mul_f32 v[52:53], v[52:53], v[60:61]
	v_pk_mul_f32 v[54:55], v[54:55], v[62:63]
	v_pk_mul_f32 v[56:57], v[48:49], v[56:57]
	v_pk_mul_f32 v[58:59], v[50:51], v[58:59]
	v_exp_f32_e32 v64, v64
	v_exp_f32_e32 v65, v65
	v_exp_f32_e32 v68, v68
	v_exp_f32_e32 v69, v69
	v_exp_f32_e32 v70, v70
	v_exp_f32_e32 v71, v71
	v_exp_f32_e32 v72, v72
	v_exp_f32_e32 v73, v73
	v_pk_mul_f32 v[52:53], v[52:53], v[190:191] op_sel:[0,1] op_sel_hi:[1,1]
	v_pk_mul_f32 v[54:55], v[54:55], v[190:191] op_sel:[0,1] op_sel_hi:[1,1]
	v_pk_mul_f32 v[56:57], v[56:57], v[190:191] op_sel:[0,1] op_sel_hi:[1,1]
	v_pk_mul_f32 v[58:59], v[58:59], v[190:191] op_sel:[0,1] op_sel_hi:[1,1]
	v_pk_add_f32 v[64:65], v[64:65], 1.0 op_sel_hi:[1,0]
	v_pk_add_f32 v[68:69], v[68:69], 1.0 op_sel_hi:[1,0]
	v_pk_add_f32 v[70:71], v[70:71], 1.0 op_sel_hi:[1,0]
	v_pk_add_f32 v[72:73], v[72:73], 1.0 op_sel_hi:[1,0]
	v_rcp_f32_e32 v64, v64
	v_rcp_f32_e32 v65, v65
	v_rcp_f32_e32 v68, v68
	v_rcp_f32_e32 v69, v69
	v_rcp_f32_e32 v70, v70
	v_rcp_f32_e32 v71, v71
	v_rcp_f32_e32 v72, v72
	v_rcp_f32_e32 v73, v73
	v_pk_mul_f32 v[52:53], v[52:53], v[64:65]
	v_pk_mul_f32 v[54:55], v[54:55], v[68:69]
	v_pk_mul_f32 v[56:57], v[56:57], v[70:71]
	v_pk_mul_f32 v[58:59], v[58:59], v[72:73]
	v_cvt_pk_bf16_f32 v48, v52, v53
	v_cvt_pk_bf16_f32 v49, v54, v55
	v_cvt_pk_bf16_f32 v50, v56, v57
	v_cvt_pk_bf16_f32 v51, v58, v59
	global_store_dwordx4 v[66:67], v[48:51], off
	s_nop 0
	s_waitcnt vmcnt(7)
; __device__ __forceinline__ unsigned cvtpk(float lo, float hi) { f32x2v_ v = {lo, hi}; bf16x2v_ b = __builtin_convertvector(v, bf16x2v_); return __builtin_bit_cast(unsigned, b); }
; __device__ __forceinline__ float row_rs(const float* ssp, int row) { const unsigned long long v = ((const unsigned long long*)ssp)[row];
;     return __builtin_amdgcn_rsqf((float)v * (1.0f / 4294967296.0f) * (1.0f / 1024.0f) + RMS_EPS); }
;     __device__ __forceinline__ void operator()(const f32x4 (&acc)[2][2][4][2], const Unit& u, int wr, int wc, int fr, int fq) const {
;     ...
;             for (int m = 0; m < 4; ++m) { const int row = row0 + ai * HALF + m * 16; const float rs = row_rs(ss, row);
;                 float hv[8];
; #pragma unroll
;                 for (int n = 0; n < 2; ++n)
; #pragma unroll
;                     for (int i = 0; i < 4; ++i) { const float g = acc[ai][0][m][n][i] * rs, uu = acc[ai][1][m][n][i] * rs;
;                         hv[n * 4 + i] = g * __builtin_amdgcn_rcpf(1.0f + __expf(-g)) * uu; }
;                 u32x4 w; w.x = cvtpk(hv[0], hv[1]); w.y = cvtpk(hv[2], hv[3]); w.z = cvtpk(hv[4], hv[5]); w.w = cvtpk(hv[6], hv[7]);
;                 *(u32x4*)(H + (size_t)row * ldh + col0) = w; }
	v_cvt_f32_u32_e32 v48, v193
	v_cvt_f32_u32_e32 v50, v192
	v_add_u32_e32 v49, 0x90, v144
	v_fmamk_f32 v48, v50, 0x2f800000, v48
	v_fmamk_f32 v48, v48, 0x3a800000, v158
	v_rsq_f32_e32 v48, v48
	v_mad_i64_i32 v[50:51], s[54:55], v49, s74, v[146:147]
	v_lshl_add_u64 v[50:51], v[50:51], 0, v[148:149]
	v_mul_f32_e32 v192, 0xbfb8aa3b, v48
	v_mul_f32_e32 v193, v48, v48
	v_pk_mul_f32 v[48:49], v[44:45], v[192:193] op_sel_hi:[1,0]
	v_pk_mul_f32 v[52:53], v[46:47], v[192:193] op_sel_hi:[1,0]
	v_pk_mul_f32 v[54:55], v[40:41], v[192:193] op_sel_hi:[1,0]
	v_pk_mul_f32 v[56:57], v[42:43], v[192:193] op_sel_hi:[1,0]
	v_pk_mul_f32 v[36:37], v[36:37], v[44:45]
	v_pk_mul_f32 v[38:39], v[38:39], v[46:47]
	v_pk_mul_f32 v[40:41], v[32:33], v[40:41]
	v_pk_mul_f32 v[42:43], v[34:35], v[42:43]
	v_exp_f32_e32 v48, v48
	v_exp_f32_e32 v49, v49
	v_exp_f32_e32 v52, v52
	v_exp_f32_e32 v53, v53
	v_exp_f32_e32 v54, v54
	v_exp_f32_e32 v55, v55
	v_exp_f32_e32 v56, v56
	v_exp_f32_e32 v57, v57
	v_pk_mul_f32 v[36:37], v[36:37], v[192:193] op_sel:[0,1] op_sel_hi:[1,1]
	v_pk_mul_f32 v[38:39], v[38:39], v[192:193] op_sel:[0,1] op_sel_hi:[1,1]
	v_pk_mul_f32 v[40:41], v[40:41], v[192:193] op_sel:[0,1] op_sel_hi:[1,1]
	v_pk_mul_f32 v[42:43], v[42:43], v[192:193] op_sel:[0,1] op_sel_hi:[1,1]
	v_pk_add_f32 v[48:49], v[48:49], 1.0 op_sel_hi:[1,0]
	v_pk_add_f32 v[52:53], v[52:53], 1.0 op_sel_hi:[1,0]
	v_pk_add_f32 v[54:55], v[54:55], 1.0 op_sel_hi:[1,0]
	v_pk_add_f32 v[56:57], v[56:57], 1.0 op_sel_hi:[1,0]
	v_rcp_f32_e32 v48, v48
	v_rcp_f32_e32 v49, v49
	v_rcp_f32_e32 v52, v52
	v_rcp_f32_e32 v53, v53
	v_rcp_f32_e32 v54, v54
	v_rcp_f32_e32 v55, v55
	v_rcp_f32_e32 v56, v56
	v_rcp_f32_e32 v57, v57
	v_pk_mul_f32 v[36:37], v[36:37], v[48:49]
	v_pk_mul_f32 v[38:39], v[38:39], v[52:53]
	v_pk_mul_f32 v[40:41], v[40:41], v[54:55]
	v_pk_mul_f32 v[42:43], v[42:43], v[56:57]
	v_cvt_pk_bf16_f32 v32, v36, v37
	v_cvt_pk_bf16_f32 v33, v38, v39
	v_cvt_pk_bf16_f32 v34, v40, v41
	v_cvt_pk_bf16_f32 v35, v42, v43
	global_store_dwordx4 v[50:51], v[32:35], off
	s_nop 0
	s_waitcnt vmcnt(7)
	v_cvt_f32_u32_e32 v32, v195
	v_cvt_f32_u32_e32 v34, v194
	v_add_u32_e32 v33, 0xa0, v144
	v_fmamk_f32 v32, v34, 0x2f800000, v32
	v_fmamk_f32 v32, v32, 0x3a800000, v158
	v_rsq_f32_e32 v32, v32
	v_mad_i64_i32 v[34:35], s[54:55], v33, s74, v[146:147]
	v_lshl_add_u64 v[34:35], v[34:35], 0, v[148:149]
	v_mul_f32_e32 v194, 0xbfb8aa3b, v32
	v_mul_f32_e32 v195, v32, v32
	v_pk_mul_f32 v[32:33], v[28:29], v[194:195] op_sel_hi:[1,0]
	v_pk_mul_f32 v[36:37], v[30:31], v[194:195] op_sel_hi:[1,0]
	v_pk_mul_f32 v[38:39], v[24:25], v[194:195] op_sel_hi:[1,0]
	v_pk_mul_f32 v[40:41], v[26:27], v[194:195] op_sel_hi:[1,0]
	v_pk_mul_f32 v[20:21], v[20:21], v[28:29]
	v_pk_mul_f32 v[22:23], v[22:23], v[30:31]
	v_pk_mul_f32 v[24:25], v[16:17], v[24:25]
	v_pk_mul_f32 v[26:27], v[18:19], v[26:27]
	v_exp_f32_e32 v32, v32
	v_exp_f32_e32 v33, v33
	v_exp_f32_e32 v36, v36
	v_exp_f32_e32 v37, v37
	v_exp_f32_e32 v38, v38
	v_exp_f32_e32 v39, v39
	v_exp_f32_e32 v40, v40
	v_exp_f32_e32 v41, v41
	v_pk_mul_f32 v[20:21], v[20:21], v[194:195] op_sel:[0,1] op_sel_hi:[1,1]
	v_pk_mul_f32 v[22:23], v[22:23], v[194:195] op_sel:[0,1] op_sel_hi:[1,1]
	v_pk_mul_f32 v[24:25], v[24:25], v[194:195] op_sel:[0,1] op_sel_hi:[1,1]
	v_pk_mul_f32 v[26:27], v[26:27], v[194:195] op_sel:[0,1] op_sel_hi:[1,1]
	v_pk_add_f32 v[32:33], v[32:33], 1.0 op_sel_hi:[1,0]
	v_pk_add_f32 v[36:37], v[36:37], 1.0 op_sel_hi:[1,0]
	v_pk_add_f32 v[38:39], v[38:39], 1.0 op_sel_hi:[1,0]
	v_pk_add_f32 v[40:41], v[40:41], 1.0 op_sel_hi:[1,0]
	v_rcp_f32_e32 v32, v32
	v_rcp_f32_e32 v33, v33
	v_rcp_f32_e32 v36, v36
	v_rcp_f32_e32 v37, v37
	v_rcp_f32_e32 v38, v38
	v_rcp_f32_e32 v39, v39
	v_rcp_f32_e32 v40, v40
	v_rcp_f32_e32 v41, v41
	v_pk_mul_f32 v[20:21], v[20:21], v[32:33]
	v_pk_mul_f32 v[22:23], v[22:23], v[36:37]
	v_pk_mul_f32 v[24:25], v[24:25], v[38:39]
	v_pk_mul_f32 v[26:27], v[26:27], v[40:41]
	v_cvt_pk_bf16_f32 v16, v20, v21
	v_cvt_pk_bf16_f32 v17, v22, v23
	v_cvt_pk_bf16_f32 v18, v24, v25
	v_cvt_pk_bf16_f32 v19, v26, v27
	global_store_dwordx4 v[34:35], v[16:19], off
	s_nop 0
	s_waitcnt vmcnt(7)
	v_cvt_f32_u32_e32 v16, v197
	v_cvt_f32_u32_e32 v18, v196
	v_add_u32_e32 v17, 0xb0, v144
	v_fmamk_f32 v16, v18, 0x2f800000, v16
	v_fmamk_f32 v16, v16, 0x3a800000, v158
	v_rsq_f32_e32 v16, v16
	v_mad_i64_i32 v[18:19], s[54:55], v17, s74, v[146:147]
	v_lshl_add_u64 v[18:19], v[18:19], 0, v[148:149]
	v_mul_f32_e32 v196, 0xbfb8aa3b, v16
	v_mul_f32_e32 v197, v16, v16
	v_pk_mul_f32 v[16:17], v[12:13], v[196:197] op_sel_hi:[1,0]
	v_pk_mul_f32 v[20:21], v[14:15], v[196:197] op_sel_hi:[1,0]
	v_pk_mul_f32 v[22:23], v[8:9], v[196:197] op_sel_hi:[1,0]
	v_pk_mul_f32 v[24:25], v[10:11], v[196:197] op_sel_hi:[1,0]
	v_pk_mul_f32 v[4:5], v[4:5], v[12:13]
	v_pk_mul_f32 v[6:7], v[6:7], v[14:15]
	v_pk_mul_f32 v[8:9], v[0:1], v[8:9]
	v_pk_mul_f32 v[10:11], v[2:3], v[10:11]
	v_exp_f32_e32 v16, v16
	v_exp_f32_e32 v17, v17
	v_exp_f32_e32 v20, v20
	v_exp_f32_e32 v21, v21
	v_exp_f32_e32 v22, v22
	v_exp_f32_e32 v23, v23
	v_exp_f32_e32 v24, v24
	v_exp_f32_e32 v25, v25
	v_pk_mul_f32 v[4:5], v[4:5], v[196:197] op_sel:[0,1] op_sel_hi:[1,1]
	v_pk_mul_f32 v[6:7], v[6:7], v[196:197] op_sel:[0,1] op_sel_hi:[1,1]
	v_pk_mul_f32 v[8:9], v[8:9], v[196:197] op_sel:[0,1] op_sel_hi:[1,1]
	v_pk_mul_f32 v[10:11], v[10:11], v[196:197] op_sel:[0,1] op_sel_hi:[1,1]
	v_pk_add_f32 v[16:17], v[16:17], 1.0 op_sel_hi:[1,0]
	v_pk_add_f32 v[20:21], v[20:21], 1.0 op_sel_hi:[1,0]
	v_pk_add_f32 v[22:23], v[22:23], 1.0 op_sel_hi:[1,0]
	v_pk_add_f32 v[24:25], v[24:25], 1.0 op_sel_hi:[1,0]
	v_rcp_f32_e32 v16, v16
	v_rcp_f32_e32 v17, v17
	v_rcp_f32_e32 v20, v20
	v_rcp_f32_e32 v21, v21
	v_rcp_f32_e32 v22, v22
	v_rcp_f32_e32 v23, v23
	v_rcp_f32_e32 v24, v24
	v_rcp_f32_e32 v25, v25
	v_pk_mul_f32 v[4:5], v[4:5], v[16:17]
	v_pk_mul_f32 v[6:7], v[6:7], v[20:21]
	v_pk_mul_f32 v[8:9], v[8:9], v[22:23]
	v_pk_mul_f32 v[10:11], v[10:11], v[24:25]
	v_cvt_pk_bf16_f32 v0, v4, v5
	v_cvt_pk_bf16_f32 v1, v6, v7
	v_cvt_pk_bf16_f32 v2, v8, v9
	v_cvt_pk_bf16_f32 v3, v10, v11
	global_store_dwordx4 v[18:19], v[0:3], off
	s_cbranch_vccnz .LBB0_1115
	s_andn2_b64 vcc, exec, s[0:1]
	s_cbranch_vccnz .LBB0_1114
	s_barrier
	s_branch .LBB0_1114

; __device__ __forceinline__ unsigned cvtpk(float lo, float hi) { f32x2v_ v = {lo, hi}; bf16x2v_ b = __builtin_convertvector(v, bf16x2v_); return __builtin_bit_cast(unsigned, b); }
; __device__ __forceinline__ float row_rs(const float* ssp, int row) { const unsigned long long v = ((const unsigned long long*)ssp)[row];
;     return __builtin_amdgcn_rsqf((float)v * (1.0f / 4294967296.0f) * (1.0f / 1024.0f) + RMS_EPS); }
;     __device__ __forceinline__ void operator()(const f32x4 (&acc)[2][2][4][2], const Unit& u, int wr, int wc, int fr, int fq) const {
;     ...
;             for (int m = 0; m < 4; ++m) { const int row = row0 + ai * HALF + m * 16; const float rs = row_rs(ss, row);
;                 float hv[8];
; #pragma unroll
;                 for (int n = 0; n < 2; ++n)
; #pragma unroll
;                     for (int i = 0; i < 4; ++i) { const float g = acc[ai][0][m][n][i] * rs, uu = acc[ai][1][m][n][i] * rs;
;                         hv[n * 4 + i] = g * __builtin_amdgcn_rcpf(1.0f + __expf(-g)) * uu; }
;                 u32x4 w; w.x = cvtpk(hv[0], hv[1]); w.y = cvtpk(hv[2], hv[3]); w.z = cvtpk(hv[4], hv[5]); w.w = cvtpk(hv[6], hv[7]);
;                 *(u32x4*)(H + (size_t)row * ldh + col0) = w; }
.LBB0_1903:
	v_lshl_or_b32 v160, s52, 7, v154
	v_ashrrev_i32_e32 v161, 31, v160
	v_or_b32_e32 v164, 16, v144
	v_ashrrev_i32_e32 v165, 31, v164
	v_lshl_add_u64 v[166:167], v[164:165], 3, s[0:1]
	v_mov_b64_e32 v[146:147], s[20:21]
	v_mad_i64_i32 v[162:163], s[38:39], v144, s51, v[146:147]
	s_andn2_b64 vcc, exec, s[4:5]
	s_mov_b64 s[4:5], -1
	s_waitcnt vmcnt(7)
	v_cvt_f32_u32_e32 v159, v183
	v_cvt_f32_u32_e32 v145, v182
	v_lshlrev_b64 v[148:149], 1, v[160:161]
	v_lshl_add_u64 v[162:163], v[162:163], 0, v[148:149]
	v_fmamk_f32 v145, v145, 0x2f800000, v159
	v_fmamk_f32 v145, v145, 0x3a800000, v158
	v_rsq_f32_e32 v160, v145
	s_nop 0
	v_mul_f32_e32 v182, 0xbfb8aa3b, v160
	v_mul_f32_e32 v183, v160, v160
	v_pk_mul_f32 v[160:161], v[124:125], v[182:183] op_sel_hi:[1,0]
	v_pk_mul_f32 v[168:169], v[126:127], v[182:183] op_sel_hi:[1,0]
	v_pk_mul_f32 v[170:171], v[120:121], v[182:183] op_sel_hi:[1,0]
	v_pk_mul_f32 v[172:173], v[122:123], v[182:183] op_sel_hi:[1,0]
	v_pk_mul_f32 v[116:117], v[116:117], v[124:125]
	v_pk_mul_f32 v[118:119], v[118:119], v[126:127]
	v_pk_mul_f32 v[120:121], v[112:113], v[120:121]
	v_pk_mul_f32 v[122:123], v[114:115], v[122:123]
	v_exp_f32_e32 v160, v160
	v_exp_f32_e32 v161, v161
	v_exp_f32_e32 v168, v168
	v_exp_f32_e32 v169, v169
	v_exp_f32_e32 v170, v170
	v_exp_f32_e32 v171, v171
	v_exp_f32_e32 v172, v172
	v_exp_f32_e32 v173, v173
	v_pk_mul_f32 v[116:117], v[116:117], v[182:183] op_sel:[0,1] op_sel_hi:[1,1]
	v_pk_mul_f32 v[118:119], v[118:119], v[182:183] op_sel:[0,1] op_sel_hi:[1,1]
	v_pk_mul_f32 v[120:121], v[120:121], v[182:183] op_sel:[0,1] op_sel_hi:[1,1]
	v_pk_mul_f32 v[122:123], v[122:123], v[182:183] op_sel:[0,1] op_sel_hi:[1,1]
	v_pk_add_f32 v[160:161], v[160:161], 1.0 op_sel_hi:[1,0]
	v_pk_add_f32 v[168:169], v[168:169], 1.0 op_sel_hi:[1,0]
	v_pk_add_f32 v[170:171], v[170:171], 1.0 op_sel_hi:[1,0]
	v_pk_add_f32 v[172:173], v[172:173], 1.0 op_sel_hi:[1,0]
	v_rcp_f32_e32 v160, v160
	v_rcp_f32_e32 v161, v161
	v_rcp_f32_e32 v168, v168
	v_rcp_f32_e32 v169, v169
	v_rcp_f32_e32 v170, v170
	v_rcp_f32_e32 v171, v171
	v_rcp_f32_e32 v172, v172
	v_rcp_f32_e32 v173, v173
	v_pk_mul_f32 v[116:117], v[116:117], v[160:161]
	v_pk_mul_f32 v[118:119], v[118:119], v[168:169]
	v_pk_mul_f32 v[120:121], v[120:121], v[170:171]
	v_pk_mul_f32 v[122:123], v[122:123], v[172:173]
	v_cvt_pk_bf16_f32 v112, v116, v117
	v_cvt_pk_bf16_f32 v113, v118, v119
	v_cvt_pk_bf16_f32 v114, v120, v121
	v_cvt_pk_bf16_f32 v115, v122, v123
	global_store_dwordx4 v[162:163], v[112:115], off
	s_nop 0
	s_nop 0
	v_or_b32_e32 v114, 32, v144
	s_waitcnt vmcnt(7)
	v_cvt_f32_u32_e32 v116, v185
	v_cvt_f32_u32_e32 v115, v184
	v_mad_i64_i32 v[112:113], s[38:39], v164, s51, v[146:147]
	v_fmamk_f32 v115, v115, 0x2f800000, v116
	v_fmamk_f32 v115, v115, 0x3a800000, v158
	v_rsq_f32_e32 v116, v115
	v_ashrrev_i32_e32 v115, 31, v114
	v_lshl_add_u64 v[118:119], v[114:115], 3, s[0:1]
	v_lshl_add_u64 v[112:113], v[112:113], 0, v[148:149]
	v_mul_f32_e32 v184, 0xbfb8aa3b, v116
	v_mul_f32_e32 v185, v116, v116
	v_pk_mul_f32 v[116:117], v[108:109], v[184:185] op_sel_hi:[1,0]
	v_pk_mul_f32 v[120:121], v[110:111], v[184:185] op_sel_hi:[1,0]
	v_pk_mul_f32 v[122:123], v[104:105], v[184:185] op_sel_hi:[1,0]
	v_pk_mul_f32 v[124:125], v[106:107], v[184:185] op_sel_hi:[1,0]
	v_pk_mul_f32 v[100:101], v[100:101], v[108:109]
	v_pk_mul_f32 v[102:103], v[102:103], v[110:111]
	v_pk_mul_f32 v[104:105], v[96:97], v[104:105]
	v_pk_mul_f32 v[106:107], v[98:99], v[106:107]
	v_exp_f32_e32 v116, v116
	v_exp_f32_e32 v117, v117
	v_exp_f32_e32 v120, v120
	v_exp_f32_e32 v121, v121
	v_exp_f32_e32 v122, v122
	v_exp_f32_e32 v123, v123
	v_exp_f32_e32 v124, v124
	v_exp_f32_e32 v125, v125
	v_pk_mul_f32 v[100:101], v[100:101], v[184:185] op_sel:[0,1] op_sel_hi:[1,1]
	v_pk_mul_f32 v[102:103], v[102:103], v[184:185] op_sel:[0,1] op_sel_hi:[1,1]
	v_pk_mul_f32 v[104:105], v[104:105], v[184:185] op_sel:[0,1] op_sel_hi:[1,1]
	v_pk_mul_f32 v[106:107], v[106:107], v[184:185] op_sel:[0,1] op_sel_hi:[1,1]
	v_pk_add_f32 v[116:117], v[116:117], 1.0 op_sel_hi:[1,0]
	v_pk_add_f32 v[120:121], v[120:121], 1.0 op_sel_hi:[1,0]
	v_pk_add_f32 v[122:123], v[122:123], 1.0 op_sel_hi:[1,0]
	v_pk_add_f32 v[124:125], v[124:125], 1.0 op_sel_hi:[1,0]
	v_rcp_f32_e32 v116, v116
	v_rcp_f32_e32 v117, v117
	v_rcp_f32_e32 v120, v120
	v_rcp_f32_e32 v121, v121
	v_rcp_f32_e32 v122, v122
	v_rcp_f32_e32 v123, v123
	v_rcp_f32_e32 v124, v124
	v_rcp_f32_e32 v125, v125
	v_pk_mul_f32 v[100:101], v[100:101], v[116:117]
	v_pk_mul_f32 v[102:103], v[102:103], v[120:121]
	v_pk_mul_f32 v[104:105], v[104:105], v[122:123]
	v_pk_mul_f32 v[106:107], v[106:107], v[124:125]
	v_cvt_pk_bf16_f32 v96, v100, v101
	v_cvt_pk_bf16_f32 v97, v102, v103
	v_cvt_pk_bf16_f32 v98, v104, v105
	v_cvt_pk_bf16_f32 v99, v106, v107
	global_store_dwordx4 v[112:113], v[96:99], off
	s_nop 0
	s_nop 0
	v_or_b32_e32 v98, 48, v144
	s_waitcnt vmcnt(7)
; __device__ __forceinline__ unsigned cvtpk(float lo, float hi) { f32x2v_ v = {lo, hi}; bf16x2v_ b = __builtin_convertvector(v, bf16x2v_); return __builtin_bit_cast(unsigned, b); }
; __device__ __forceinline__ float row_rs(const float* ssp, int row) { const unsigned long long v = ((const unsigned long long*)ssp)[row];
;     return __builtin_amdgcn_rsqf((float)v * (1.0f / 4294967296.0f) * (1.0f / 1024.0f) + RMS_EPS); }
;     __device__ __forceinline__ void operator()(const f32x4 (&acc)[2][2][4][2], const Unit& u, int wr, int wc, int fr, int fq) const {
;     ...
;             for (int m = 0; m < 4; ++m) { const int row = row0 + ai * HALF + m * 16; const float rs = row_rs(ss, row);
;                 float hv[8];
; #pragma unroll
;                 for (int n = 0; n < 2; ++n)
; #pragma unroll
;                     for (int i = 0; i < 4; ++i) { const float g = acc[ai][0][m][n][i] * rs, uu = acc[ai][1][m][n][i] * rs;
;                         hv[n * 4 + i] = g * __builtin_amdgcn_rcpf(1.0f + __expf(-g)) * uu; }
;                 u32x4 w; w.x = cvtpk(hv[0], hv[1]); w.y = cvtpk(hv[2], hv[3]); w.z = cvtpk(hv[4], hv[5]); w.w = cvtpk(hv[6], hv[7]);
;                 *(u32x4*)(H + (size_t)row * ldh + col0) = w; }
	v_cvt_f32_u32_e32 v100, v187
	v_cvt_f32_u32_e32 v99, v186
	v_mad_i64_i32 v[96:97], s[38:39], v114, s51, v[146:147]
	v_fmamk_f32 v99, v99, 0x2f800000, v100
	v_fmamk_f32 v99, v99, 0x3a800000, v158
	v_rsq_f32_e32 v100, v99
	v_ashrrev_i32_e32 v99, 31, v98
	v_lshl_add_u64 v[102:103], v[98:99], 3, s[0:1]
	v_lshl_add_u64 v[96:97], v[96:97], 0, v[148:149]
	v_mul_f32_e32 v186, 0xbfb8aa3b, v100
	v_mul_f32_e32 v187, v100, v100
	v_pk_mul_f32 v[100:101], v[92:93], v[186:187] op_sel_hi:[1,0]
	v_pk_mul_f32 v[104:105], v[94:95], v[186:187] op_sel_hi:[1,0]
	v_pk_mul_f32 v[106:107], v[88:89], v[186:187] op_sel_hi:[1,0]
	v_pk_mul_f32 v[108:109], v[90:91], v[186:187] op_sel_hi:[1,0]
	v_pk_mul_f32 v[84:85], v[84:85], v[92:93]
	v_pk_mul_f32 v[86:87], v[86:87], v[94:95]
	v_pk_mul_f32 v[88:89], v[80:81], v[88:89]
	v_pk_mul_f32 v[90:91], v[82:83], v[90:91]
	v_exp_f32_e32 v100, v100
	v_exp_f32_e32 v101, v101
	v_exp_f32_e32 v104, v104
	v_exp_f32_e32 v105, v105
	v_exp_f32_e32 v106, v106
	v_exp_f32_e32 v107, v107
	v_exp_f32_e32 v108, v108
	v_exp_f32_e32 v109, v109
	v_pk_mul_f32 v[84:85], v[84:85], v[186:187] op_sel:[0,1] op_sel_hi:[1,1]
	v_pk_mul_f32 v[86:87], v[86:87], v[186:187] op_sel:[0,1] op_sel_hi:[1,1]
	v_pk_mul_f32 v[88:89], v[88:89], v[186:187] op_sel:[0,1] op_sel_hi:[1,1]
	v_pk_mul_f32 v[90:91], v[90:91], v[186:187] op_sel:[0,1] op_sel_hi:[1,1]
	v_pk_add_f32 v[100:101], v[100:101], 1.0 op_sel_hi:[1,0]
	v_pk_add_f32 v[104:105], v[104:105], 1.0 op_sel_hi:[1,0]
	v_pk_add_f32 v[106:107], v[106:107], 1.0 op_sel_hi:[1,0]
	v_pk_add_f32 v[108:109], v[108:109], 1.0 op_sel_hi:[1,0]
	v_rcp_f32_e32 v100, v100
	v_rcp_f32_e32 v101, v101
	v_rcp_f32_e32 v104, v104
	v_rcp_f32_e32 v105, v105
	v_rcp_f32_e32 v106, v106
	v_rcp_f32_e32 v107, v107
	v_rcp_f32_e32 v108, v108
	v_rcp_f32_e32 v109, v109
	v_pk_mul_f32 v[84:85], v[84:85], v[100:101]
	v_pk_mul_f32 v[86:87], v[86:87], v[104:105]
	v_pk_mul_f32 v[88:89], v[88:89], v[106:107]
	v_pk_mul_f32 v[90:91], v[90:91], v[108:109]
	v_cvt_pk_bf16_f32 v80, v84, v85
	v_cvt_pk_bf16_f32 v81, v86, v87
	v_cvt_pk_bf16_f32 v82, v88, v89
	v_cvt_pk_bf16_f32 v83, v90, v91
	global_store_dwordx4 v[96:97], v[80:83], off
	s_nop 0
	s_waitcnt vmcnt(7)
	v_cvt_f32_u32_e32 v80, v189
	v_cvt_f32_u32_e32 v81, v188
	v_mad_i64_i32 v[82:83], s[38:39], v98, s51, v[146:147]
	v_fmamk_f32 v80, v81, 0x2f800000, v80
	v_fmamk_f32 v80, v80, 0x3a800000, v158
	v_rsq_f32_e32 v80, v80
	v_lshl_add_u64 v[82:83], v[82:83], 0, v[148:149]
	v_mul_f32_e32 v188, 0xbfb8aa3b, v80
	v_mul_f32_e32 v189, v80, v80
	v_pk_mul_f32 v[80:81], v[76:77], v[188:189] op_sel_hi:[1,0]
	v_pk_mul_f32 v[84:85], v[78:79], v[188:189] op_sel_hi:[1,0]
	v_pk_mul_f32 v[86:87], v[72:73], v[188:189] op_sel_hi:[1,0]
	v_pk_mul_f32 v[88:89], v[74:75], v[188:189] op_sel_hi:[1,0]
	v_pk_mul_f32 v[68:69], v[68:69], v[76:77]
	v_pk_mul_f32 v[70:71], v[70:71], v[78:79]
	v_pk_mul_f32 v[72:73], v[64:65], v[72:73]
	v_pk_mul_f32 v[74:75], v[66:67], v[74:75]
	v_exp_f32_e32 v80, v80
	v_exp_f32_e32 v81, v81
	v_exp_f32_e32 v84, v84
	v_exp_f32_e32 v85, v85
	v_exp_f32_e32 v86, v86
	v_exp_f32_e32 v87, v87
	v_exp_f32_e32 v88, v88
	v_exp_f32_e32 v89, v89
	v_pk_mul_f32 v[68:69], v[68:69], v[188:189] op_sel:[0,1] op_sel_hi:[1,1]
	v_pk_mul_f32 v[70:71], v[70:71], v[188:189] op_sel:[0,1] op_sel_hi:[1,1]
	v_pk_mul_f32 v[72:73], v[72:73], v[188:189] op_sel:[0,1] op_sel_hi:[1,1]
	v_pk_mul_f32 v[74:75], v[74:75], v[188:189] op_sel:[0,1] op_sel_hi:[1,1]
	v_pk_add_f32 v[80:81], v[80:81], 1.0 op_sel_hi:[1,0]
	v_pk_add_f32 v[84:85], v[84:85], 1.0 op_sel_hi:[1,0]
	v_pk_add_f32 v[86:87], v[86:87], 1.0 op_sel_hi:[1,0]
	v_pk_add_f32 v[88:89], v[88:89], 1.0 op_sel_hi:[1,0]
	v_rcp_f32_e32 v80, v80
	v_rcp_f32_e32 v81, v81
	v_rcp_f32_e32 v84, v84
	v_rcp_f32_e32 v85, v85
	v_rcp_f32_e32 v86, v86
	v_rcp_f32_e32 v87, v87
	v_rcp_f32_e32 v88, v88
	v_rcp_f32_e32 v89, v89
	v_pk_mul_f32 v[68:69], v[68:69], v[80:81]
	v_pk_mul_f32 v[70:71], v[70:71], v[84:85]
	v_pk_mul_f32 v[72:73], v[72:73], v[86:87]
	v_pk_mul_f32 v[74:75], v[74:75], v[88:89]
	v_cvt_pk_bf16_f32 v64, v68, v69
	v_cvt_pk_bf16_f32 v65, v70, v71
	v_cvt_pk_bf16_f32 v66, v72, v73
	v_cvt_pk_bf16_f32 v67, v74, v75
	global_store_dwordx4 v[82:83], v[64:67], off
	s_nop 0
	s_waitcnt vmcnt(7)
	v_cvt_f32_u32_e32 v64, v191
	v_cvt_f32_u32_e32 v66, v190
	v_add_u32_e32 v65, 0x80, v144
	v_fmamk_f32 v64, v66, 0x2f800000, v64
	v_fmamk_f32 v64, v64, 0x3a800000, v158
	v_rsq_f32_e32 v64, v64
	v_mad_i64_i32 v[66:67], s[38:39], v65, s51, v[146:147]
	v_lshl_add_u64 v[66:67], v[66:67], 0, v[148:149]
	v_mul_f32_e32 v190, 0xbfb8aa3b, v64
	v_mul_f32_e32 v191, v64, v64
	v_pk_mul_f32 v[64:65], v[60:61], v[190:191] op_sel_hi:[1,0]
	v_pk_mul_f32 v[68:69], v[62:63], v[190:191] op_sel_hi:[1,0]
	v_pk_mul_f32 v[70:71], v[56:57], v[190:191] op_sel_hi:[1,0]
	v_pk_mul_f32 v[72:73], v[58:59], v[190:191] op_sel_hi:[1,0]
	v_pk_mul_f32 v[52:53], v[52:53], v[60:61]
	v_pk_mul_f32 v[54:55], v[54:55], v[62:63]
	v_pk_mul_f32 v[56:57], v[48:49], v[56:57]
	v_pk_mul_f32 v[58:59], v[50:51], v[58:59]
	v_exp_f32_e32 v64, v64
	v_exp_f32_e32 v65, v65
	v_exp_f32_e32 v68, v68
	v_exp_f32_e32 v69, v69
	v_exp_f32_e32 v70, v70
	v_exp_f32_e32 v71, v71
	v_exp_f32_e32 v72, v72
	v_exp_f32_e32 v73, v73
	v_pk_mul_f32 v[52:53], v[52:53], v[190:191] op_sel:[0,1] op_sel_hi:[1,1]
	v_pk_mul_f32 v[54:55], v[54:55], v[190:191] op_sel:[0,1] op_sel_hi:[1,1]
	v_pk_mul_f32 v[56:57], v[56:57], v[190:191] op_sel:[0,1] op_sel_hi:[1,1]
	v_pk_mul_f32 v[58:59], v[58:59], v[190:191] op_sel:[0,1] op_sel_hi:[1,1]
	v_pk_add_f32 v[64:65], v[64:65], 1.0 op_sel_hi:[1,0]
	v_pk_add_f32 v[68:69], v[68:69], 1.0 op_sel_hi:[1,0]
	v_pk_add_f32 v[70:71], v[70:71], 1.0 op_sel_hi:[1,0]
	v_pk_add_f32 v[72:73], v[72:73], 1.0 op_sel_hi:[1,0]
	v_rcp_f32_e32 v64, v64
	v_rcp_f32_e32 v65, v65
	v_rcp_f32_e32 v68, v68
	v_rcp_f32_e32 v69, v69
	v_rcp_f32_e32 v70, v70
	v_rcp_f32_e32 v71, v71
	v_rcp_f32_e32 v72, v72
	v_rcp_f32_e32 v73, v73
	v_pk_mul_f32 v[52:53], v[52:53], v[64:65]
	v_pk_mul_f32 v[54:55], v[54:55], v[68:69]
	v_pk_mul_f32 v[56:57], v[56:57], v[70:71]
	v_pk_mul_f32 v[58:59], v[58:59], v[72:73]
	v_cvt_pk_bf16_f32 v48, v52, v53
	v_cvt_pk_bf16_f32 v49, v54, v55
	v_cvt_pk_bf16_f32 v50, v56, v57
	v_cvt_pk_bf16_f32 v51, v58, v59
	global_store_dwordx4 v[66:67], v[48:51], off
	s_nop 0
	s_waitcnt vmcnt(7)
; __device__ __forceinline__ unsigned cvtpk(float lo, float hi) { f32x2v_ v = {lo, hi}; bf16x2v_ b = __builtin_convertvector(v, bf16x2v_); return __builtin_bit_cast(unsigned, b); }
; __device__ __forceinline__ float row_rs(const float* ssp, int row) { const unsigned long long v = ((const unsigned long long*)ssp)[row];
;     return __builtin_amdgcn_rsqf((float)v * (1.0f / 4294967296.0f) * (1.0f / 1024.0f) + RMS_EPS); }
;     __device__ __forceinline__ void operator()(const f32x4 (&acc)[2][2][4][2], const Unit& u, int wr, int wc, int fr, int fq) const {
;     ...
;             for (int m = 0; m < 4; ++m) { const int row = row0 + ai * HALF + m * 16; const float rs = row_rs(ss, row);
;                 float hv[8];
; #pragma unroll
;                 for (int n = 0; n < 2; ++n)
; #pragma unroll
;                     for (int i = 0; i < 4; ++i) { const float g = acc[ai][0][m][n][i] * rs, uu = acc[ai][1][m][n][i] * rs;
;                         hv[n * 4 + i] = g * __builtin_amdgcn_rcpf(1.0f + __expf(-g)) * uu; }
;                 u32x4 w; w.x = cvtpk(hv[0], hv[1]); w.y = cvtpk(hv[2], hv[3]); w.z = cvtpk(hv[4], hv[5]); w.w = cvtpk(hv[6], hv[7]);
;                 *(u32x4*)(H + (size_t)row * ldh + col0) = w; }
	v_cvt_f32_u32_e32 v48, v193
	v_cvt_f32_u32_e32 v50, v192
	v_add_u32_e32 v49, 0x90, v144
	v_fmamk_f32 v48, v50, 0x2f800000, v48
	v_fmamk_f32 v48, v48, 0x3a800000, v158
	v_rsq_f32_e32 v48, v48
	v_mad_i64_i32 v[50:51], s[38:39], v49, s51, v[146:147]
	v_lshl_add_u64 v[50:51], v[50:51], 0, v[148:149]
	v_mul_f32_e32 v192, 0xbfb8aa3b, v48
	v_mul_f32_e32 v193, v48, v48
	v_pk_mul_f32 v[48:49], v[44:45], v[192:193] op_sel_hi:[1,0]
	v_pk_mul_f32 v[52:53], v[46:47], v[192:193] op_sel_hi:[1,0]
	v_pk_mul_f32 v[54:55], v[40:41], v[192:193] op_sel_hi:[1,0]
	v_pk_mul_f32 v[56:57], v[42:43], v[192:193] op_sel_hi:[1,0]
	v_pk_mul_f32 v[36:37], v[36:37], v[44:45]
	v_pk_mul_f32 v[38:39], v[38:39], v[46:47]
	v_pk_mul_f32 v[40:41], v[32:33], v[40:41]
	v_pk_mul_f32 v[42:43], v[34:35], v[42:43]
	v_exp_f32_e32 v48, v48
	v_exp_f32_e32 v49, v49
	v_exp_f32_e32 v52, v52
	v_exp_f32_e32 v53, v53
	v_exp_f32_e32 v54, v54
	v_exp_f32_e32 v55, v55
	v_exp_f32_e32 v56, v56
	v_exp_f32_e32 v57, v57
	v_pk_mul_f32 v[36:37], v[36:37], v[192:193] op_sel:[0,1] op_sel_hi:[1,1]
	v_pk_mul_f32 v[38:39], v[38:39], v[192:193] op_sel:[0,1] op_sel_hi:[1,1]
	v_pk_mul_f32 v[40:41], v[40:41], v[192:193] op_sel:[0,1] op_sel_hi:[1,1]
	v_pk_mul_f32 v[42:43], v[42:43], v[192:193] op_sel:[0,1] op_sel_hi:[1,1]
	v_pk_add_f32 v[48:49], v[48:49], 1.0 op_sel_hi:[1,0]
	v_pk_add_f32 v[52:53], v[52:53], 1.0 op_sel_hi:[1,0]
	v_pk_add_f32 v[54:55], v[54:55], 1.0 op_sel_hi:[1,0]
	v_pk_add_f32 v[56:57], v[56:57], 1.0 op_sel_hi:[1,0]
	v_rcp_f32_e32 v48, v48
	v_rcp_f32_e32 v49, v49
	v_rcp_f32_e32 v52, v52
	v_rcp_f32_e32 v53, v53
	v_rcp_f32_e32 v54, v54
	v_rcp_f32_e32 v55, v55
	v_rcp_f32_e32 v56, v56
	v_rcp_f32_e32 v57, v57
	v_pk_mul_f32 v[36:37], v[36:37], v[48:49]
	v_pk_mul_f32 v[38:39], v[38:39], v[52:53]
	v_pk_mul_f32 v[40:41], v[40:41], v[54:55]
	v_pk_mul_f32 v[42:43], v[42:43], v[56:57]
	v_cvt_pk_bf16_f32 v32, v36, v37
	v_cvt_pk_bf16_f32 v33, v38, v39
	v_cvt_pk_bf16_f32 v34, v40, v41
	v_cvt_pk_bf16_f32 v35, v42, v43
	global_store_dwordx4 v[50:51], v[32:35], off
	s_nop 0
	s_waitcnt vmcnt(7)
	v_cvt_f32_u32_e32 v32, v195
	v_cvt_f32_u32_e32 v34, v194
	v_add_u32_e32 v33, 0xa0, v144
	v_fmamk_f32 v32, v34, 0x2f800000, v32
	v_fmamk_f32 v32, v32, 0x3a800000, v158
	v_rsq_f32_e32 v32, v32
	v_mad_i64_i32 v[34:35], s[38:39], v33, s51, v[146:147]
	v_lshl_add_u64 v[34:35], v[34:35], 0, v[148:149]
	v_mul_f32_e32 v194, 0xbfb8aa3b, v32
	v_mul_f32_e32 v195, v32, v32
	v_pk_mul_f32 v[32:33], v[28:29], v[194:195] op_sel_hi:[1,0]
	v_pk_mul_f32 v[36:37], v[30:31], v[194:195] op_sel_hi:[1,0]
	v_pk_mul_f32 v[38:39], v[24:25], v[194:195] op_sel_hi:[1,0]
	v_pk_mul_f32 v[40:41], v[26:27], v[194:195] op_sel_hi:[1,0]
	v_pk_mul_f32 v[20:21], v[20:21], v[28:29]
	v_pk_mul_f32 v[22:23], v[22:23], v[30:31]
	v_pk_mul_f32 v[24:25], v[16:17], v[24:25]
	v_pk_mul_f32 v[26:27], v[18:19], v[26:27]
	v_exp_f32_e32 v32, v32
	v_exp_f32_e32 v33, v33
	v_exp_f32_e32 v36, v36
	v_exp_f32_e32 v37, v37
	v_exp_f32_e32 v38, v38
	v_exp_f32_e32 v39, v39
	v_exp_f32_e32 v40, v40
	v_exp_f32_e32 v41, v41
	v_pk_mul_f32 v[20:21], v[20:21], v[194:195] op_sel:[0,1] op_sel_hi:[1,1]
	v_pk_mul_f32 v[22:23], v[22:23], v[194:195] op_sel:[0,1] op_sel_hi:[1,1]
	v_pk_mul_f32 v[24:25], v[24:25], v[194:195] op_sel:[0,1] op_sel_hi:[1,1]
	v_pk_mul_f32 v[26:27], v[26:27], v[194:195] op_sel:[0,1] op_sel_hi:[1,1]
	v_pk_add_f32 v[32:33], v[32:33], 1.0 op_sel_hi:[1,0]
	v_pk_add_f32 v[36:37], v[36:37], 1.0 op_sel_hi:[1,0]
	v_pk_add_f32 v[38:39], v[38:39], 1.0 op_sel_hi:[1,0]
	v_pk_add_f32 v[40:41], v[40:41], 1.0 op_sel_hi:[1,0]
	v_rcp_f32_e32 v32, v32
	v_rcp_f32_e32 v33, v33
	v_rcp_f32_e32 v36, v36
	v_rcp_f32_e32 v37, v37
	v_rcp_f32_e32 v38, v38
	v_rcp_f32_e32 v39, v39
	v_rcp_f32_e32 v40, v40
	v_rcp_f32_e32 v41, v41
	v_pk_mul_f32 v[20:21], v[20:21], v[32:33]
	v_pk_mul_f32 v[22:23], v[22:23], v[36:37]
	v_pk_mul_f32 v[24:25], v[24:25], v[38:39]
	v_pk_mul_f32 v[26:27], v[26:27], v[40:41]
	v_cvt_pk_bf16_f32 v16, v20, v21
	v_cvt_pk_bf16_f32 v17, v22, v23
	v_cvt_pk_bf16_f32 v18, v24, v25
	v_cvt_pk_bf16_f32 v19, v26, v27
	global_store_dwordx4 v[34:35], v[16:19], off
	s_nop 0
	s_waitcnt vmcnt(7)
	v_cvt_f32_u32_e32 v16, v197
	v_cvt_f32_u32_e32 v18, v196
	v_add_u32_e32 v17, 0xb0, v144
	v_fmamk_f32 v16, v18, 0x2f800000, v16
	v_fmamk_f32 v16, v16, 0x3a800000, v158
	v_rsq_f32_e32 v16, v16
	v_mad_i64_i32 v[18:19], s[38:39], v17, s51, v[146:147]
	v_lshl_add_u64 v[18:19], v[18:19], 0, v[148:149]
	v_mul_f32_e32 v196, 0xbfb8aa3b, v16
	v_mul_f32_e32 v197, v16, v16
	v_pk_mul_f32 v[16:17], v[12:13], v[196:197] op_sel_hi:[1,0]
	v_pk_mul_f32 v[20:21], v[14:15], v[196:197] op_sel_hi:[1,0]
	v_pk_mul_f32 v[22:23], v[8:9], v[196:197] op_sel_hi:[1,0]
	v_pk_mul_f32 v[24:25], v[10:11], v[196:197] op_sel_hi:[1,0]
	v_pk_mul_f32 v[4:5], v[4:5], v[12:13]
	v_pk_mul_f32 v[6:7], v[6:7], v[14:15]
	v_pk_mul_f32 v[8:9], v[0:1], v[8:9]
	v_pk_mul_f32 v[10:11], v[2:3], v[10:11]
	v_exp_f32_e32 v16, v16
	v_exp_f32_e32 v17, v17
	v_exp_f32_e32 v20, v20
	v_exp_f32_e32 v21, v21
	v_exp_f32_e32 v22, v22
	v_exp_f32_e32 v23, v23
	v_exp_f32_e32 v24, v24
	v_exp_f32_e32 v25, v25
	v_pk_mul_f32 v[4:5], v[4:5], v[196:197] op_sel:[0,1] op_sel_hi:[1,1]
	v_pk_mul_f32 v[6:7], v[6:7], v[196:197] op_sel:[0,1] op_sel_hi:[1,1]
	v_pk_mul_f32 v[8:9], v[8:9], v[196:197] op_sel:[0,1] op_sel_hi:[1,1]
	v_pk_mul_f32 v[10:11], v[10:11], v[196:197] op_sel:[0,1] op_sel_hi:[1,1]
	v_pk_add_f32 v[16:17], v[16:17], 1.0 op_sel_hi:[1,0]
	v_pk_add_f32 v[20:21], v[20:21], 1.0 op_sel_hi:[1,0]
	v_pk_add_f32 v[22:23], v[22:23], 1.0 op_sel_hi:[1,0]
	v_pk_add_f32 v[24:25], v[24:25], 1.0 op_sel_hi:[1,0]
	v_rcp_f32_e32 v16, v16
	v_rcp_f32_e32 v17, v17
	v_rcp_f32_e32 v20, v20
	v_rcp_f32_e32 v21, v21
	v_rcp_f32_e32 v22, v22
	v_rcp_f32_e32 v23, v23
	v_rcp_f32_e32 v24, v24
	v_rcp_f32_e32 v25, v25
	v_pk_mul_f32 v[4:5], v[4:5], v[16:17]
	v_pk_mul_f32 v[6:7], v[6:7], v[20:21]
	v_pk_mul_f32 v[8:9], v[8:9], v[22:23]
	v_pk_mul_f32 v[10:11], v[10:11], v[24:25]
	v_cvt_pk_bf16_f32 v0, v4, v5
	v_cvt_pk_bf16_f32 v1, v6, v7
	v_cvt_pk_bf16_f32 v2, v8, v9
	v_cvt_pk_bf16_f32 v3, v10, v11
	global_store_dwordx4 v[18:19], v[0:3], off
	s_cbranch_vccnz .LBB0_1896
	s_andn2_b64 vcc, exec, s[6:7]
	s_cbranch_vccnz .LBB0_1895
	s_barrier
	s_branch .LBB0_1895
